# attention: PV computed transposed (each lane owns an output row): rescale without LDS exchange, hand-written epilogue with permlane-packed 16-byte stores
# speedup vs baseline: 1.0066x; 1.0066x over previous
.Lat_u1x_bar:
	s_barrier
	s_lshr_b32 s4, s69, 1
	s_sub_u32 s4, s52, s4
	s_cmp_gt_i32 s4, s87
	s_cbranch_scc1 .Lat_u1x_noqk
	s_mul_i32 s53, s48, 0x3000
	v_add_u32_e32 v158, s53, v146
	ds_read_b128 v[196:199], v158
	ds_read_b128 v[200:203], v158 offset:512
	ds_read_b128 v[204:207], v158 offset:2048
	ds_read_b128 v[208:211], v158 offset:2560
	ds_read_b128 v[212:215], v158 offset:4096
	ds_read_b128 v[230:233], v158 offset:4608
	ds_read_b128 v[234:237], v158 offset:6144
	ds_read_b128 v[164:167], v158 offset:6656
	ds_read_b128 v[168:171], v158 offset:8192
	ds_read_b128 v[172:175], v158 offset:8704
	ds_read_b128 v[148:151], v158 offset:10240
	ds_read_b128 v[152:155], v158 offset:10752
	s_lshl_b32 s4, s50, 13
	s_add_i32 s4, s4, 0x6000
	s_and_b32 s4, s4, 0x6000
	v_add_u32_e32 v159, s4, v144
	v_mov_b32_e32 v156, 0
	v_mov_b32_e32 v157, 0
	s_waitcnt lgkmcnt(11)
	v_mfma_f32_32x32x16_bf16 v[238:253], v[196:199], v[100:103], v[104:119]
	ds_read_b64_tr_b16 v[196:197], v159 offset:36864
	ds_read_b64_tr_b16 v[198:199], v159 offset:37376
	v_exp_f32_e32 v64, v64
	v_exp_f32_e32 v65, v65
	v_add_f32_e32 v156, v156, v64
	v_add_f32_e32 v156, v156, v65
	v_cvt_pk_bf16_f32 v64, v64, v65
	s_waitcnt lgkmcnt(12)
	v_mfma_f32_32x32x16_bf16 v[180:195], v[200:203], v[100:103], v[104:119]
	ds_read_b64_tr_b16 v[200:201], v159 offset:37888
	ds_read_b64_tr_b16 v[202:203], v159 offset:38400
	v_exp_f32_e32 v66, v66
	v_exp_f32_e32 v67, v67
	v_add_f32_e32 v157, v157, v66
	v_add_f32_e32 v157, v157, v67
	v_cvt_pk_bf16_f32 v65, v66, v67
	s_waitcnt lgkmcnt(13)
	v_mfma_f32_32x32x16_bf16 v[238:253], v[204:207], v[96:99], v[238:253]
	ds_read_b64_tr_b16 v[204:205], v159 offset:38912
	ds_read_b64_tr_b16 v[206:207], v159 offset:39424
	v_exp_f32_e32 v68, v68
	v_exp_f32_e32 v69, v69
	v_add_f32_e32 v156, v156, v68
	v_add_f32_e32 v156, v156, v69
	v_cvt_pk_bf16_f32 v66, v68, v69
	s_waitcnt lgkmcnt(14)
	v_mfma_f32_32x32x16_bf16 v[180:195], v[208:211], v[96:99], v[180:195]
	ds_read_b64_tr_b16 v[208:209], v159 offset:39936
	ds_read_b64_tr_b16 v[210:211], v159 offset:40448
	v_exp_f32_e32 v70, v70
	v_exp_f32_e32 v71, v71
	v_add_f32_e32 v157, v157, v70
	v_add_f32_e32 v157, v157, v71
	v_cvt_pk_bf16_f32 v67, v70, v71
	s_waitcnt lgkmcnt(15)
	v_mfma_f32_32x32x16_bf16 v[238:253], v[212:215], v[92:95], v[238:253]
	ds_read_b64_tr_b16 v[212:213], v159 offset:40960
	ds_read_b64_tr_b16 v[214:215], v159 offset:41472
	v_exp_f32_e32 v72, v72
	v_exp_f32_e32 v73, v73
	v_add_f32_e32 v156, v156, v72
	v_add_f32_e32 v156, v156, v73
	v_cvt_pk_bf16_f32 v68, v72, v73
	s_waitcnt lgkmcnt(15)
	v_mfma_f32_32x32x16_bf16 v[180:195], v[230:233], v[92:95], v[180:195]
	ds_read_b64_tr_b16 v[230:231], v159 offset:41984
	ds_read_b64_tr_b16 v[232:233], v159 offset:42496
	v_exp_f32_e32 v74, v74
	v_exp_f32_e32 v75, v75
	v_add_f32_e32 v157, v157, v74
	v_add_f32_e32 v157, v157, v75
	v_cvt_pk_bf16_f32 v69, v74, v75
	s_waitcnt lgkmcnt(15)
	v_mfma_f32_32x32x16_bf16 v[238:253], v[234:237], v[88:91], v[238:253]
	ds_read_b64_tr_b16 v[234:235], v159 offset:43008
	ds_read_b64_tr_b16 v[236:237], v159 offset:43520
	v_exp_f32_e32 v76, v76
	v_exp_f32_e32 v77, v77
	v_add_f32_e32 v156, v156, v76
	v_add_f32_e32 v156, v156, v77
	v_cvt_pk_bf16_f32 v70, v76, v77
	s_waitcnt lgkmcnt(15)
	v_mfma_f32_32x32x16_bf16 v[180:195], v[164:167], v[88:91], v[180:195]
	ds_read_b64_tr_b16 v[164:165], v159 offset:44032
	ds_read_b64_tr_b16 v[166:167], v159 offset:44544
	v_exp_f32_e32 v78, v78
	v_exp_f32_e32 v79, v79
	v_add_f32_e32 v157, v157, v78
	v_add_f32_e32 v157, v157, v79
	v_cvt_pk_bf16_f32 v71, v78, v79
	s_waitcnt lgkmcnt(15)
	v_mfma_f32_32x32x16_bf16 v[238:253], v[168:171], v[84:87], v[238:253]
	v_exp_f32_e32 v48, v48
	v_exp_f32_e32 v49, v49
	v_add_f32_e32 v156, v156, v48
	v_add_f32_e32 v156, v156, v49
	v_cvt_pk_bf16_f32 v48, v48, v49
	s_waitcnt lgkmcnt(15)
	v_mfma_f32_32x32x16_bf16 v[180:195], v[172:175], v[84:87], v[180:195]
	v_exp_f32_e32 v50, v50
	v_exp_f32_e32 v51, v51
	v_add_f32_e32 v157, v157, v50
	v_add_f32_e32 v157, v157, v51
	v_cvt_pk_bf16_f32 v49, v50, v51
	s_waitcnt lgkmcnt(15)
	v_mfma_f32_32x32x16_bf16 v[238:253], v[148:151], v[80:83], v[238:253]
	v_exp_f32_e32 v52, v52
	v_exp_f32_e32 v53, v53
	v_add_f32_e32 v156, v156, v52
	v_add_f32_e32 v156, v156, v53
	v_cvt_pk_bf16_f32 v50, v52, v53
	s_waitcnt lgkmcnt(15)
	v_mfma_f32_32x32x16_bf16 v[180:195], v[152:155], v[80:83], v[180:195]
	v_exp_f32_e32 v54, v54
	v_exp_f32_e32 v55, v55
	v_add_f32_e32 v157, v157, v54
	v_add_f32_e32 v157, v157, v55
	v_cvt_pk_bf16_f32 v51, v54, v55
	s_nop 1
	s_waitcnt lgkmcnt(0)
	v_mfma_f32_32x32x16_bf16 v[16:31], v[196:199], v[64:67], v[16:31]
	v_exp_f32_e32 v56, v56
	v_exp_f32_e32 v57, v57
	v_add_f32_e32 v156, v156, v56
	v_add_f32_e32 v156, v156, v57
	v_cvt_pk_bf16_f32 v52, v56, v57
	s_nop 1
	v_mfma_f32_32x32x16_bf16 v[32:47], v[212:215], v[64:67], v[32:47]
	s_mul_i32 s53, s48, 0x3000
	s_add_i32 s4, s52, 2
	s_cmp_ge_u32 s4, s86
	s_cbranch_scc1 .Lat_u1x_nodma
	s_add_i32 s4, s53, 0xffffd000
	s_cmp_lg_u32 s48, 0
	s_cselect_b32 s4, s4, 0x6000
	s_add_i32 s5, s4, s97
	s_mov_b32 m0, s5
	s_add_i32 s4, s4, s72
	global_load_lds_dwordx4 v[126:127], off
	s_mov_b32 m0, s4
	s_cmp_lt_u32 s69, 4
	s_cbranch_scc0 .Lat_u1x_nok2
	global_load_lds_dwordx4 v[14:15], off

; __device__ __forceinline__ void cmask(f32x16& p0, f32x16& p1, int jb, int qrel, int hi) {
;     const float NEG = -INFINITY; const int kb = 64 * jb + 4 * hi;
; #pragma unroll
;     for (int r = 0; r < 16; ++r) { const int kv = kb + (r & 3) + 8 * (r >> 2); if (kv > qrel) p0[r] = NEG; if (kv + 32 > qrel) p1[r] = NEG; }
; }
.Lat_u1x_nodma:
	v_lshl_add_u64 v[126:127], v[126:127], 0, s[34:35]
	v_lshl_add_u64 v[14:15], v[14:15], 0, s[20:21]
	v_lshl_add_u64 v[124:125], v[124:125], 0, s[34:35]
	v_exp_f32_e32 v58, v58
	v_exp_f32_e32 v59, v59
	v_add_f32_e32 v157, v157, v58
	v_add_f32_e32 v157, v157, v59
	v_cvt_pk_bf16_f32 v53, v58, v59
	s_nop 1
	v_mfma_f32_32x32x16_bf16 v[16:31], v[200:203], v[68:71], v[16:31]
	v_exp_f32_e32 v60, v60
	v_exp_f32_e32 v61, v61
	v_add_f32_e32 v156, v156, v60
	v_add_f32_e32 v156, v156, v61
	v_cvt_pk_bf16_f32 v54, v60, v61
	s_nop 1
	v_mfma_f32_32x32x16_bf16 v[32:47], v[230:233], v[68:71], v[32:47]
	v_exp_f32_e32 v62, v62
	v_exp_f32_e32 v63, v63
	v_add_f32_e32 v157, v157, v62
	v_add_f32_e32 v157, v157, v63
	v_cvt_pk_bf16_f32 v55, v62, v63
	s_nop 1
	v_mfma_f32_32x32x16_bf16 v[16:31], v[204:207], v[48:51], v[16:31]
	v_mfma_f32_32x32x16_bf16 v[32:47], v[234:237], v[48:51], v[32:47]
	v_mfma_f32_32x32x16_bf16 v[16:31], v[208:211], v[52:55], v[16:31]
	v_mfma_f32_32x32x16_bf16 v[32:47], v[164:167], v[52:55], v[32:47]
	v_add_f32_e32 v156, v156, v157
	v_add_f32_e32 v128, v128, v156
	s_cmp_lt_u32 s52, s87
	s_cbranch_scc1 .Lat_u1x_nomask
	s_sub_i32 s4, s52, s87
	s_lshl_b32 s4, s4, 6
	s_nop 7
	s_nop 7
	v_lshl_add_u32 v147, v141, 2, s4
	v_sub_u32_e32 v147, v145, v147
	v_cmp_gt_i32_e32 vcc, 0, v147
	s_nop 1
	v_cndmask_b32_e32 v238, v238, v220, vcc
	v_cmp_gt_i32_e32 vcc, 1, v147
	s_nop 1
	v_cndmask_b32_e32 v239, v239, v220, vcc
	v_cmp_gt_i32_e32 vcc, 2, v147
	s_nop 1
	v_cndmask_b32_e32 v240, v240, v220, vcc
	v_cmp_gt_i32_e32 vcc, 3, v147
	s_nop 1
	v_cndmask_b32_e32 v241, v241, v220, vcc
	v_cmp_gt_i32_e32 vcc, 8, v147
	s_nop 1
	v_cndmask_b32_e32 v242, v242, v220, vcc
	v_cmp_gt_i32_e32 vcc, 9, v147
	s_nop 1
	v_cndmask_b32_e32 v243, v243, v220, vcc
	v_cmp_gt_i32_e32 vcc, 10, v147
	s_nop 1
	v_cndmask_b32_e32 v244, v244, v220, vcc
	v_cmp_gt_i32_e32 vcc, 11, v147
	s_nop 1
	v_cndmask_b32_e32 v245, v245, v220, vcc
	v_cmp_gt_i32_e32 vcc, 16, v147
	s_nop 1
	v_cndmask_b32_e32 v246, v246, v220, vcc
	v_cmp_gt_i32_e32 vcc, 17, v147
	s_nop 1
	v_cndmask_b32_e32 v247, v247, v220, vcc
	v_cmp_gt_i32_e32 vcc, 18, v147
	s_nop 1
	v_cndmask_b32_e32 v248, v248, v220, vcc
	v_cmp_gt_i32_e32 vcc, 19, v147
	s_nop 1
	v_cndmask_b32_e32 v249, v249, v220, vcc
	v_cmp_gt_i32_e32 vcc, 24, v147
	s_nop 1
	v_cndmask_b32_e32 v250, v250, v220, vcc
	v_cmp_gt_i32_e32 vcc, 25, v147
	s_nop 1
	v_cndmask_b32_e32 v251, v251, v220, vcc
	v_cmp_gt_i32_e32 vcc, 26, v147
	s_nop 1
	v_cndmask_b32_e32 v252, v252, v220, vcc
	v_cmp_gt_i32_e32 vcc, 27, v147
	s_nop 1
	v_cndmask_b32_e32 v253, v253, v220, vcc
	v_cmp_gt_i32_e32 vcc, 32, v147
	s_nop 1
	v_cndmask_b32_e32 v180, v180, v220, vcc
	v_cmp_gt_i32_e32 vcc, 33, v147
	s_nop 1
	v_cndmask_b32_e32 v181, v181, v220, vcc
	v_cmp_gt_i32_e32 vcc, 34, v147
	s_nop 1
	v_cndmask_b32_e32 v182, v182, v220, vcc
	v_cmp_gt_i32_e32 vcc, 35, v147
	s_nop 1
	v_cndmask_b32_e32 v183, v183, v220, vcc
	v_cmp_gt_i32_e32 vcc, 40, v147
	s_nop 1
	v_cndmask_b32_e32 v184, v184, v220, vcc
	v_cmp_gt_i32_e32 vcc, 41, v147
	s_nop 1
	v_cndmask_b32_e32 v185, v185, v220, vcc
	v_cmp_gt_i32_e32 vcc, 42, v147
	s_nop 1
	v_cndmask_b32_e32 v186, v186, v220, vcc
	v_cmp_gt_i32_e32 vcc, 43, v147
	s_nop 1
	v_cndmask_b32_e32 v187, v187, v220, vcc
	v_cmp_gt_i32_e32 vcc, 48, v147
	s_nop 1
	v_cndmask_b32_e32 v188, v188, v220, vcc
	v_cmp_gt_i32_e32 vcc, 49, v147
	s_nop 1
	v_cndmask_b32_e32 v189, v189, v220, vcc
	v_cmp_gt_i32_e32 vcc, 50, v147
	s_nop 1
	v_cndmask_b32_e32 v190, v190, v220, vcc
	v_cmp_gt_i32_e32 vcc, 51, v147
	s_nop 1
	v_cndmask_b32_e32 v191, v191, v220, vcc
	v_cmp_gt_i32_e32 vcc, 56, v147
	s_nop 1
	v_cndmask_b32_e32 v192, v192, v220, vcc
	v_cmp_gt_i32_e32 vcc, 57, v147
	s_nop 1
	v_cndmask_b32_e32 v193, v193, v220, vcc
	v_cmp_gt_i32_e32 vcc, 58, v147
	s_nop 1
	v_cndmask_b32_e32 v194, v194, v220, vcc
	v_cmp_gt_i32_e32 vcc, 59, v147
	s_nop 1
	v_cndmask_b32_e32 v195, v195, v220, vcc

.Lat_u1y_bar:
	s_barrier
	s_lshr_b32 s4, s69, 1
	s_sub_u32 s4, s52, s4
	s_cmp_gt_i32 s4, s87
	s_cbranch_scc1 .Lat_u1y_noqk
	s_mul_i32 s53, s48, 0x3000
	v_add_u32_e32 v158, s53, v146
	ds_read_b128 v[196:199], v158
	ds_read_b128 v[200:203], v158 offset:512
	ds_read_b128 v[204:207], v158 offset:2048
	ds_read_b128 v[208:211], v158 offset:2560
	ds_read_b128 v[212:215], v158 offset:4096
	ds_read_b128 v[230:233], v158 offset:4608
	ds_read_b128 v[234:237], v158 offset:6144
	ds_read_b128 v[164:167], v158 offset:6656
	ds_read_b128 v[168:171], v158 offset:8192
	ds_read_b128 v[172:175], v158 offset:8704
	ds_read_b128 v[148:151], v158 offset:10240
	ds_read_b128 v[152:155], v158 offset:10752
	s_lshl_b32 s4, s50, 13
	s_add_i32 s4, s4, 0x6000
	s_and_b32 s4, s4, 0x6000
	v_add_u32_e32 v159, s4, v144
	v_mov_b32_e32 v156, 0
	v_mov_b32_e32 v157, 0
	s_waitcnt lgkmcnt(11)
	v_mfma_f32_32x32x16_bf16 v[64:79], v[196:199], v[100:103], v[104:119]
	ds_read_b64_tr_b16 v[196:197], v159 offset:36864
	ds_read_b64_tr_b16 v[198:199], v159 offset:37376
	v_exp_f32_e32 v238, v238
	v_exp_f32_e32 v239, v239
	v_add_f32_e32 v156, v156, v238
	v_add_f32_e32 v156, v156, v239
	v_cvt_pk_bf16_f32 v238, v238, v239
	s_waitcnt lgkmcnt(12)
	v_mfma_f32_32x32x16_bf16 v[48:63], v[200:203], v[100:103], v[104:119]
	ds_read_b64_tr_b16 v[200:201], v159 offset:37888
	ds_read_b64_tr_b16 v[202:203], v159 offset:38400
	v_exp_f32_e32 v240, v240
	v_exp_f32_e32 v241, v241
	v_add_f32_e32 v157, v157, v240
	v_add_f32_e32 v157, v157, v241
	v_cvt_pk_bf16_f32 v239, v240, v241
	s_waitcnt lgkmcnt(13)
	v_mfma_f32_32x32x16_bf16 v[64:79], v[204:207], v[96:99], v[64:79]
	ds_read_b64_tr_b16 v[204:205], v159 offset:38912
	ds_read_b64_tr_b16 v[206:207], v159 offset:39424
	v_exp_f32_e32 v242, v242
	v_exp_f32_e32 v243, v243
	v_add_f32_e32 v156, v156, v242
	v_add_f32_e32 v156, v156, v243
	v_cvt_pk_bf16_f32 v240, v242, v243
	s_waitcnt lgkmcnt(14)
	v_mfma_f32_32x32x16_bf16 v[48:63], v[208:211], v[96:99], v[48:63]
	ds_read_b64_tr_b16 v[208:209], v159 offset:39936
	ds_read_b64_tr_b16 v[210:211], v159 offset:40448
	v_exp_f32_e32 v244, v244
	v_exp_f32_e32 v245, v245
	v_add_f32_e32 v157, v157, v244
	v_add_f32_e32 v157, v157, v245
	v_cvt_pk_bf16_f32 v241, v244, v245
	s_waitcnt lgkmcnt(15)
	v_mfma_f32_32x32x16_bf16 v[64:79], v[212:215], v[92:95], v[64:79]
	ds_read_b64_tr_b16 v[212:213], v159 offset:40960
	ds_read_b64_tr_b16 v[214:215], v159 offset:41472
	v_exp_f32_e32 v246, v246
	v_exp_f32_e32 v247, v247
	v_add_f32_e32 v156, v156, v246
	v_add_f32_e32 v156, v156, v247
	v_cvt_pk_bf16_f32 v242, v246, v247
	s_waitcnt lgkmcnt(15)
	v_mfma_f32_32x32x16_bf16 v[48:63], v[230:233], v[92:95], v[48:63]
	ds_read_b64_tr_b16 v[230:231], v159 offset:41984
	ds_read_b64_tr_b16 v[232:233], v159 offset:42496
	v_exp_f32_e32 v248, v248
	v_exp_f32_e32 v249, v249
	v_add_f32_e32 v157, v157, v248
	v_add_f32_e32 v157, v157, v249
	v_cvt_pk_bf16_f32 v243, v248, v249
	s_waitcnt lgkmcnt(15)
	v_mfma_f32_32x32x16_bf16 v[64:79], v[234:237], v[88:91], v[64:79]
	ds_read_b64_tr_b16 v[234:235], v159 offset:43008
	ds_read_b64_tr_b16 v[236:237], v159 offset:43520
	v_exp_f32_e32 v250, v250
	v_exp_f32_e32 v251, v251
	v_add_f32_e32 v156, v156, v250
	v_add_f32_e32 v156, v156, v251
	v_cvt_pk_bf16_f32 v244, v250, v251
	s_waitcnt lgkmcnt(15)
	v_mfma_f32_32x32x16_bf16 v[48:63], v[164:167], v[88:91], v[48:63]
	ds_read_b64_tr_b16 v[164:165], v159 offset:44032
	ds_read_b64_tr_b16 v[166:167], v159 offset:44544
	v_exp_f32_e32 v252, v252
	v_exp_f32_e32 v253, v253
	v_add_f32_e32 v157, v157, v252
	v_add_f32_e32 v157, v157, v253
	v_cvt_pk_bf16_f32 v245, v252, v253
	s_waitcnt lgkmcnt(15)
	v_mfma_f32_32x32x16_bf16 v[64:79], v[168:171], v[84:87], v[64:79]
	v_exp_f32_e32 v180, v180
	v_exp_f32_e32 v181, v181
	v_add_f32_e32 v156, v156, v180
	v_add_f32_e32 v156, v156, v181
	v_cvt_pk_bf16_f32 v180, v180, v181
	s_waitcnt lgkmcnt(15)
	v_mfma_f32_32x32x16_bf16 v[48:63], v[172:175], v[84:87], v[48:63]
	v_exp_f32_e32 v182, v182
	v_exp_f32_e32 v183, v183
	v_add_f32_e32 v157, v157, v182
	v_add_f32_e32 v157, v157, v183
	v_cvt_pk_bf16_f32 v181, v182, v183
	s_waitcnt lgkmcnt(15)
	v_mfma_f32_32x32x16_bf16 v[64:79], v[148:151], v[80:83], v[64:79]
	v_exp_f32_e32 v184, v184
	v_exp_f32_e32 v185, v185
	v_add_f32_e32 v156, v156, v184
	v_add_f32_e32 v156, v156, v185
	v_cvt_pk_bf16_f32 v182, v184, v185
	s_waitcnt lgkmcnt(15)
	v_mfma_f32_32x32x16_bf16 v[48:63], v[152:155], v[80:83], v[48:63]
	v_exp_f32_e32 v186, v186
	v_exp_f32_e32 v187, v187
	v_add_f32_e32 v157, v157, v186
	v_add_f32_e32 v157, v157, v187
	v_cvt_pk_bf16_f32 v183, v186, v187
	s_nop 1
	s_waitcnt lgkmcnt(0)
	v_mfma_f32_32x32x16_bf16 v[16:31], v[196:199], v[238:241], v[16:31]
	v_exp_f32_e32 v188, v188
	v_exp_f32_e32 v189, v189
	v_add_f32_e32 v156, v156, v188
	v_add_f32_e32 v156, v156, v189
	v_cvt_pk_bf16_f32 v184, v188, v189
	s_nop 1
	v_mfma_f32_32x32x16_bf16 v[32:47], v[212:215], v[238:241], v[32:47]
	s_mul_i32 s53, s48, 0x3000
	s_add_i32 s4, s52, 2
	s_cmp_ge_u32 s4, s86
	s_cbranch_scc1 .Lat_u1y_nodma
	s_add_i32 s4, s53, 0xffffd000
	s_cmp_lg_u32 s48, 0
	s_cselect_b32 s4, s4, 0x6000
	s_add_i32 s5, s4, s97
	s_mov_b32 m0, s5
	s_add_i32 s4, s4, s72
	global_load_lds_dwordx4 v[126:127], off
	s_mov_b32 m0, s4
	s_cmp_lt_u32 s69, 4
	s_cbranch_scc0 .Lat_u1y_nok2
	global_load_lds_dwordx4 v[14:15], off

; __device__ __forceinline__ void cmask(f32x16& p0, f32x16& p1, int jb, int qrel, int hi) {
;     const float NEG = -INFINITY; const int kb = 64 * jb + 4 * hi;
; #pragma unroll
;     for (int r = 0; r < 16; ++r) { const int kv = kb + (r & 3) + 8 * (r >> 2); if (kv > qrel) p0[r] = NEG; if (kv + 32 > qrel) p1[r] = NEG; }
; }
.Lat_u1y_nodma:
	v_lshl_add_u64 v[126:127], v[126:127], 0, s[34:35]
	v_lshl_add_u64 v[14:15], v[14:15], 0, s[20:21]
	v_lshl_add_u64 v[124:125], v[124:125], 0, s[34:35]
	v_exp_f32_e32 v190, v190
	v_exp_f32_e32 v191, v191
	v_add_f32_e32 v157, v157, v190
	v_add_f32_e32 v157, v157, v191
	v_cvt_pk_bf16_f32 v185, v190, v191
	s_nop 1
	v_mfma_f32_32x32x16_bf16 v[16:31], v[200:203], v[242:245], v[16:31]
	v_exp_f32_e32 v192, v192
	v_exp_f32_e32 v193, v193
	v_add_f32_e32 v156, v156, v192
	v_add_f32_e32 v156, v156, v193
	v_cvt_pk_bf16_f32 v186, v192, v193
	s_nop 1
	v_mfma_f32_32x32x16_bf16 v[32:47], v[230:233], v[242:245], v[32:47]
	v_exp_f32_e32 v194, v194
	v_exp_f32_e32 v195, v195
	v_add_f32_e32 v157, v157, v194
	v_add_f32_e32 v157, v157, v195
	v_cvt_pk_bf16_f32 v187, v194, v195
	s_nop 1
	v_mfma_f32_32x32x16_bf16 v[16:31], v[204:207], v[180:183], v[16:31]
	v_mfma_f32_32x32x16_bf16 v[32:47], v[234:237], v[180:183], v[32:47]
	v_mfma_f32_32x32x16_bf16 v[16:31], v[208:211], v[184:187], v[16:31]
	v_mfma_f32_32x32x16_bf16 v[32:47], v[164:167], v[184:187], v[32:47]
	v_add_f32_e32 v156, v156, v157
	v_add_f32_e32 v128, v128, v156
	s_cmp_lt_u32 s52, s87
	s_cbranch_scc1 .Lat_u1y_nomask
	s_sub_i32 s4, s52, s87
	s_lshl_b32 s4, s4, 6
	s_nop 7
	s_nop 7
	v_lshl_add_u32 v147, v141, 2, s4
	v_sub_u32_e32 v147, v145, v147
	v_cmp_gt_i32_e32 vcc, 0, v147
	s_nop 1
	v_cndmask_b32_e32 v64, v64, v220, vcc
	v_cmp_gt_i32_e32 vcc, 1, v147
	s_nop 1
	v_cndmask_b32_e32 v65, v65, v220, vcc
	v_cmp_gt_i32_e32 vcc, 2, v147
	s_nop 1
	v_cndmask_b32_e32 v66, v66, v220, vcc
	v_cmp_gt_i32_e32 vcc, 3, v147
	s_nop 1
	v_cndmask_b32_e32 v67, v67, v220, vcc
	v_cmp_gt_i32_e32 vcc, 8, v147
	s_nop 1
	v_cndmask_b32_e32 v68, v68, v220, vcc
	v_cmp_gt_i32_e32 vcc, 9, v147
	s_nop 1
	v_cndmask_b32_e32 v69, v69, v220, vcc
	v_cmp_gt_i32_e32 vcc, 10, v147
	s_nop 1
	v_cndmask_b32_e32 v70, v70, v220, vcc
	v_cmp_gt_i32_e32 vcc, 11, v147
	s_nop 1
	v_cndmask_b32_e32 v71, v71, v220, vcc
	v_cmp_gt_i32_e32 vcc, 16, v147
	s_nop 1
	v_cndmask_b32_e32 v72, v72, v220, vcc
	v_cmp_gt_i32_e32 vcc, 17, v147
	s_nop 1
	v_cndmask_b32_e32 v73, v73, v220, vcc
	v_cmp_gt_i32_e32 vcc, 18, v147
	s_nop 1
	v_cndmask_b32_e32 v74, v74, v220, vcc
	v_cmp_gt_i32_e32 vcc, 19, v147
	s_nop 1
	v_cndmask_b32_e32 v75, v75, v220, vcc
	v_cmp_gt_i32_e32 vcc, 24, v147
	s_nop 1
	v_cndmask_b32_e32 v76, v76, v220, vcc
	v_cmp_gt_i32_e32 vcc, 25, v147
	s_nop 1
	v_cndmask_b32_e32 v77, v77, v220, vcc
	v_cmp_gt_i32_e32 vcc, 26, v147
	s_nop 1
	v_cndmask_b32_e32 v78, v78, v220, vcc
	v_cmp_gt_i32_e32 vcc, 27, v147
	s_nop 1
	v_cndmask_b32_e32 v79, v79, v220, vcc
	v_cmp_gt_i32_e32 vcc, 32, v147
	s_nop 1
	v_cndmask_b32_e32 v48, v48, v220, vcc
	v_cmp_gt_i32_e32 vcc, 33, v147
	s_nop 1
	v_cndmask_b32_e32 v49, v49, v220, vcc
	v_cmp_gt_i32_e32 vcc, 34, v147
	s_nop 1
	v_cndmask_b32_e32 v50, v50, v220, vcc
	v_cmp_gt_i32_e32 vcc, 35, v147
	s_nop 1
	v_cndmask_b32_e32 v51, v51, v220, vcc
	v_cmp_gt_i32_e32 vcc, 40, v147
	s_nop 1
	v_cndmask_b32_e32 v52, v52, v220, vcc
	v_cmp_gt_i32_e32 vcc, 41, v147
	s_nop 1
	v_cndmask_b32_e32 v53, v53, v220, vcc
	v_cmp_gt_i32_e32 vcc, 42, v147
	s_nop 1
	v_cndmask_b32_e32 v54, v54, v220, vcc
	v_cmp_gt_i32_e32 vcc, 43, v147
	s_nop 1
	v_cndmask_b32_e32 v55, v55, v220, vcc
	v_cmp_gt_i32_e32 vcc, 48, v147
	s_nop 1
	v_cndmask_b32_e32 v56, v56, v220, vcc
	v_cmp_gt_i32_e32 vcc, 49, v147
	s_nop 1
	v_cndmask_b32_e32 v57, v57, v220, vcc
	v_cmp_gt_i32_e32 vcc, 50, v147
	s_nop 1
	v_cndmask_b32_e32 v58, v58, v220, vcc
	v_cmp_gt_i32_e32 vcc, 51, v147
	s_nop 1
	v_cndmask_b32_e32 v59, v59, v220, vcc
	v_cmp_gt_i32_e32 vcc, 56, v147
	s_nop 1
	v_cndmask_b32_e32 v60, v60, v220, vcc
	v_cmp_gt_i32_e32 vcc, 57, v147
	s_nop 1
	v_cndmask_b32_e32 v61, v61, v220, vcc
	v_cmp_gt_i32_e32 vcc, 58, v147
	s_nop 1
	v_cndmask_b32_e32 v62, v62, v220, vcc
	v_cmp_gt_i32_e32 vcc, 59, v147
	s_nop 1
	v_cndmask_b32_e32 v63, v63, v220, vcc

; #define LAS __attribute__((address_space(3)))
; __device__ __forceinline__ int crow(int r, int hi) { return (r & 3) + 8 * (r >> 2) + 4 * hi; }
; __device__ __forceinline__ unsigned cvtpk_s(float lo, float hi) { f32x2 v = {lo, hi}; typedef __bf16 bf16x2_t __attribute__((ext_vector_type(2))); bf16x2_t b = __builtin_convertvector(v, bf16x2_t); return __builtin_bit_cast(unsigned, b); }
; __device__ __forceinline__ void attn_unit(int b, int h, int qb, const bf16* Q, const bf16* __restrict__ Kn, const bf16* __restrict__ Kpe, const bf16* __restrict__ V, bf16* O, float* ASS, LAS char* shm) {
;     ...
;     { auto rr = __builtin_amdgcn_permlane32_swap(__float_as_uint(l_run), __float_as_uint(l_run), false, false); l_run = __uint_as_float(rr[0]) + __uint_as_float(rr[1]); }
;     if (hi == 0) wsf[32 + r32] = l_run; asm volatile("s_waitcnt lgkmcnt(0)" ::: "memory");
;     float rli[16];
; #pragma unroll
;     for (int r = 0; r < 16; ++r) rli[r] = __builtin_amdgcn_rcpf(wsf[32 + crow(r, hi)]);
;     bf16* Ow = O + (rowbase + q0 + wid * QBLK) * OP + h * 64;
;     { LAS unsigned short* stg = (LAS unsigned short*)(shm + LDS_OST) + wid * 2048;
; #pragma unroll
;       for (int r = 0; r < 16; ++r) { const int orow = crow(r, hi);
; #pragma unroll
;           for (int d0 = 0; d0 < 2; ++d0) stg[orow * 64 + d0 * 32 + r32] = (unsigned short)(cvtpk_s(o[d0][r] * rli[r], 0.f) & 0xffffu); }
.Lat_u1_tail:
	s_waitcnt lgkmcnt(0)
	s_lshr_b32 s4, s69, 1
	s_sub_u32 s4, s52, s4
	s_sub_u32 s4, s4, 1
	s_cmp_gt_i32 s4, s87
	s_cbranch_scc1 .Lat_u1t_skip
	s_lshl_b32 s4, s50, 13
	s_add_i32 s4, s4, 0x6000
	s_and_b32 s4, s4, 0x6000
	v_add_u32_e32 v159, s4, v144
	ds_read_b64_tr_b16 v[196:197], v159 offset:36864
	ds_read_b64_tr_b16 v[198:199], v159 offset:37376
	ds_read_b64_tr_b16 v[200:201], v159 offset:37888
	ds_read_b64_tr_b16 v[202:203], v159 offset:38400
	ds_read_b64_tr_b16 v[204:205], v159 offset:38912
	ds_read_b64_tr_b16 v[206:207], v159 offset:39424
	ds_read_b64_tr_b16 v[208:209], v159 offset:39936
	ds_read_b64_tr_b16 v[210:211], v159 offset:40448
	ds_read_b64_tr_b16 v[212:213], v159 offset:40960
	ds_read_b64_tr_b16 v[214:215], v159 offset:41472
	ds_read_b64_tr_b16 v[230:231], v159 offset:41984
	ds_read_b64_tr_b16 v[232:233], v159 offset:42496
	ds_read_b64_tr_b16 v[234:235], v159 offset:43008
	ds_read_b64_tr_b16 v[236:237], v159 offset:43520
	ds_read_b64_tr_b16 v[164:165], v159 offset:44032
	ds_read_b64_tr_b16 v[166:167], v159 offset:44544
	v_mov_b32_e32 v156, 0
	v_mov_b32_e32 v157, 0
	v_exp_f32_e32 v238, v238
	v_exp_f32_e32 v239, v239
	v_add_f32_e32 v156, v156, v238
	v_add_f32_e32 v156, v156, v239
	v_cvt_pk_bf16_f32 v238, v238, v239
	v_exp_f32_e32 v240, v240
	v_exp_f32_e32 v241, v241
	v_add_f32_e32 v157, v157, v240
	v_add_f32_e32 v157, v157, v241
	v_cvt_pk_bf16_f32 v239, v240, v241
	v_exp_f32_e32 v242, v242
	v_exp_f32_e32 v243, v243
	v_add_f32_e32 v156, v156, v242
	v_add_f32_e32 v156, v156, v243
	v_cvt_pk_bf16_f32 v240, v242, v243
	v_exp_f32_e32 v244, v244
	v_exp_f32_e32 v245, v245
	v_add_f32_e32 v157, v157, v244
	v_add_f32_e32 v157, v157, v245
	v_cvt_pk_bf16_f32 v241, v244, v245
	v_exp_f32_e32 v246, v246
	v_exp_f32_e32 v247, v247
	v_add_f32_e32 v156, v156, v246
	v_add_f32_e32 v156, v156, v247
	v_cvt_pk_bf16_f32 v242, v246, v247
	v_exp_f32_e32 v248, v248
	v_exp_f32_e32 v249, v249
	v_add_f32_e32 v157, v157, v248
	v_add_f32_e32 v157, v157, v249
	v_cvt_pk_bf16_f32 v243, v248, v249
	v_exp_f32_e32 v250, v250
	v_exp_f32_e32 v251, v251
	v_add_f32_e32 v156, v156, v250
	v_add_f32_e32 v156, v156, v251
	v_cvt_pk_bf16_f32 v244, v250, v251
	v_exp_f32_e32 v252, v252
	v_exp_f32_e32 v253, v253
	v_add_f32_e32 v157, v157, v252
	v_add_f32_e32 v157, v157, v253
	v_cvt_pk_bf16_f32 v245, v252, v253
	v_exp_f32_e32 v180, v180
	v_exp_f32_e32 v181, v181
	v_add_f32_e32 v156, v156, v180
	v_add_f32_e32 v156, v156, v181
	v_cvt_pk_bf16_f32 v180, v180, v181
	v_exp_f32_e32 v182, v182
	v_exp_f32_e32 v183, v183
	v_add_f32_e32 v157, v157, v182
	v_add_f32_e32 v157, v157, v183
	v_cvt_pk_bf16_f32 v181, v182, v183
	v_exp_f32_e32 v184, v184
	v_exp_f32_e32 v185, v185
	v_add_f32_e32 v156, v156, v184
	v_add_f32_e32 v156, v156, v185
	v_cvt_pk_bf16_f32 v182, v184, v185
	v_exp_f32_e32 v186, v186
	v_exp_f32_e32 v187, v187
	v_add_f32_e32 v157, v157, v186
	v_add_f32_e32 v157, v157, v187
	v_cvt_pk_bf16_f32 v183, v186, v187
	v_exp_f32_e32 v188, v188
	v_exp_f32_e32 v189, v189
	v_add_f32_e32 v156, v156, v188
	v_add_f32_e32 v156, v156, v189
	v_cvt_pk_bf16_f32 v184, v188, v189
	v_exp_f32_e32 v190, v190
	v_exp_f32_e32 v191, v191
	v_add_f32_e32 v157, v157, v190
	v_add_f32_e32 v157, v157, v191
	v_cvt_pk_bf16_f32 v185, v190, v191
	v_exp_f32_e32 v192, v192
	v_exp_f32_e32 v193, v193
	v_add_f32_e32 v156, v156, v192
	v_add_f32_e32 v156, v156, v193
	v_cvt_pk_bf16_f32 v186, v192, v193
	v_exp_f32_e32 v194, v194
	v_exp_f32_e32 v195, v195
	v_add_f32_e32 v157, v157, v194
	v_add_f32_e32 v157, v157, v195
	v_cvt_pk_bf16_f32 v187, v194, v195
	v_add_f32_e32 v156, v156, v157
	v_add_f32_e32 v128, v128, v156
	s_waitcnt lgkmcnt(0)
	v_mfma_f32_32x32x16_bf16 v[16:31], v[196:199], v[238:241], v[16:31]
	v_mfma_f32_32x32x16_bf16 v[32:47], v[212:215], v[238:241], v[32:47]
	v_mfma_f32_32x32x16_bf16 v[16:31], v[200:203], v[242:245], v[16:31]
	v_mfma_f32_32x32x16_bf16 v[32:47], v[230:233], v[242:245], v[32:47]
	v_mfma_f32_32x32x16_bf16 v[16:31], v[204:207], v[180:183], v[16:31]
	v_mfma_f32_32x32x16_bf16 v[32:47], v[234:237], v[180:183], v[32:47]
	v_mfma_f32_32x32x16_bf16 v[16:31], v[208:211], v[184:187], v[16:31]
	v_mfma_f32_32x32x16_bf16 v[32:47], v[164:167], v[184:187], v[32:47]
.Lat_u1t_skip:
	s_nop 7
	s_nop 7
	v_mov_b32_e32 v212, v128
	s_nop 1
	v_permlane32_swap_b32_e32 v128, v212
	s_nop 0
	v_add_f32_e32 v128, v128, v212
	v_rcp_f32_e32 v212, v128
	v_mov_b32_e32 v213, 0
	v_mul_f32_e32 v230, v16, v212
	v_mul_f32_e32 v231, v17, v212
	v_mul_f32_e32 v232, v18, v212
	v_mul_f32_e32 v233, v19, v212
	v_cvt_pk_bf16_f32 v196, v230, v231
	v_cvt_pk_bf16_f32 v197, v232, v233
	v_mul_f32_e32 v230, v20, v212
	v_mul_f32_e32 v231, v21, v212
	v_mul_f32_e32 v232, v22, v212
	v_mul_f32_e32 v233, v23, v212
	v_cvt_pk_bf16_f32 v198, v230, v231
	v_cvt_pk_bf16_f32 v199, v232, v233
	v_mul_f32_e32 v230, v24, v212
	v_mul_f32_e32 v231, v25, v212
	v_mul_f32_e32 v232, v26, v212
	v_mul_f32_e32 v233, v27, v212
	v_cvt_pk_bf16_f32 v200, v230, v231
	v_cvt_pk_bf16_f32 v201, v232, v233
	v_mul_f32_e32 v230, v28, v212
	v_mul_f32_e32 v231, v29, v212
	v_mul_f32_e32 v232, v30, v212
	v_mul_f32_e32 v233, v31, v212
	v_cvt_pk_bf16_f32 v202, v230, v231
	v_cvt_pk_bf16_f32 v203, v232, v233
	v_mul_f32_e32 v230, v32, v212
	v_mul_f32_e32 v231, v33, v212
	v_mul_f32_e32 v232, v34, v212
	v_mul_f32_e32 v233, v35, v212
	v_cvt_pk_bf16_f32 v204, v230, v231
	v_cvt_pk_bf16_f32 v205, v232, v233
	v_mul_f32_e32 v230, v36, v212
	v_mul_f32_e32 v231, v37, v212
	v_mul_f32_e32 v232, v38, v212
	v_mul_f32_e32 v233, v39, v212
	v_cvt_pk_bf16_f32 v206, v230, v231
	v_cvt_pk_bf16_f32 v207, v232, v233
	v_mul_f32_e32 v230, v40, v212
	v_mul_f32_e32 v231, v41, v212
	v_mul_f32_e32 v232, v42, v212
; #define LAS __attribute__((address_space(3)))
; __device__ __forceinline__ unsigned cvtpk_s(float lo, float hi) { f32x2 v = {lo, hi}; typedef __bf16 bf16x2_t __attribute__((ext_vector_type(2))); bf16x2_t b = __builtin_convertvector(v, bf16x2_t); return __builtin_bit_cast(unsigned, b); }
; __device__ __forceinline__ void attn_unit(int b, int h, int qb, const bf16* Q, const bf16* __restrict__ Kn, const bf16* __restrict__ Kpe, const bf16* __restrict__ V, bf16* O, float* ASS, LAS char* shm) {
;     ...
;           for (int d0 = 0; d0 < 2; ++d0) stg[orow * 64 + d0 * 32 + r32] = (unsigned short)(cvtpk_s(o[d0][r] * rli[r], 0.f) & 0xffffu); }
;       asm volatile("s_waitcnt lgkmcnt(0)" ::: "memory");
; #pragma unroll
;       for (int i = 0; i < 4; ++i) { const int row = i * 8 + (lane >> 3), ch = lane & 7; const u32x4 v = *(const LAS u32x4*)(stg + row * 64 + ch * 8); *(u32x4*)(Ow + (long)row * OP + ch * 8) = v;
;           float sq = 0.f;
; #pragma unroll
;           for (int k = 0; k < 4; ++k) { const float a = __uint_as_float(v[k] << 16), bq = __uint_as_float(v[k] & 0xffff0000u); sq += a * a + bq * bq; }
;           sq += __shfl_xor(sq, 1); sq += __shfl_xor(sq, 2); sq += __shfl_xor(sq, 4);
;           if (ch == 0) ASS[(rowbase + q0 + wid * QBLK + row) * 8 + h] = sq; } }
	v_mul_f32_e32 v233, v43, v212
	v_cvt_pk_bf16_f32 v208, v230, v231
	v_cvt_pk_bf16_f32 v209, v232, v233
	v_mul_f32_e32 v230, v44, v212
	v_mul_f32_e32 v231, v45, v212
	v_mul_f32_e32 v232, v46, v212
	v_mul_f32_e32 v233, v47, v212
	v_cvt_pk_bf16_f32 v210, v230, v231
	v_cvt_pk_bf16_f32 v211, v232, v233
	s_nop 1
	v_permlane32_swap_b32_e32 v196, v198
	v_permlane32_swap_b32_e32 v197, v199
	v_permlane32_swap_b32_e32 v200, v202
	v_permlane32_swap_b32_e32 v201, v203
	v_permlane32_swap_b32_e32 v204, v206
	v_permlane32_swap_b32_e32 v205, v207
	v_permlane32_swap_b32_e32 v208, v210
	v_permlane32_swap_b32_e32 v209, v211
	s_lshl_b64 s[4:5], s[66:67], 11
	s_add_u32 s4, s4, s80
	s_addc_u32 s5, s5, s81
	s_lshl_b32 s53, s68, 7
	s_add_u32 s4, s4, s53
	s_addc_u32 s5, s5, 0
	v_lshlrev_b32_e32 v234, 11, v140
	v_lshl_or_b32 v234, v141, 4, v234
	global_store_dwordx4 v234, v[196:199], s[4:5]
	global_store_dwordx4 v234, v[200:203], s[4:5] offset:32
	global_store_dwordx4 v234, v[204:207], s[4:5] offset:64
	global_store_dwordx4 v234, v[208:211], s[4:5] offset:96
	v_lshlrev_b32_e32 v230, 16, v196
	v_and_b32_e32 v231, 0xffff0000, v196
	v_fmac_f32_e32 v213, v230, v230
	v_fmac_f32_e32 v213, v231, v231
	v_lshlrev_b32_e32 v230, 16, v197
	v_and_b32_e32 v231, 0xffff0000, v197
	v_fmac_f32_e32 v213, v230, v230
	v_fmac_f32_e32 v213, v231, v231
	v_lshlrev_b32_e32 v230, 16, v198
	v_and_b32_e32 v231, 0xffff0000, v198
	v_fmac_f32_e32 v213, v230, v230
	v_fmac_f32_e32 v213, v231, v231
	v_lshlrev_b32_e32 v230, 16, v199
	v_and_b32_e32 v231, 0xffff0000, v199
	v_fmac_f32_e32 v213, v230, v230
	v_fmac_f32_e32 v213, v231, v231
	v_lshlrev_b32_e32 v230, 16, v200
	v_and_b32_e32 v231, 0xffff0000, v200
	v_fmac_f32_e32 v213, v230, v230
	v_fmac_f32_e32 v213, v231, v231
	v_lshlrev_b32_e32 v230, 16, v201
	v_and_b32_e32 v231, 0xffff0000, v201
	v_fmac_f32_e32 v213, v230, v230
	v_fmac_f32_e32 v213, v231, v231
	v_lshlrev_b32_e32 v230, 16, v202
	v_and_b32_e32 v231, 0xffff0000, v202
	v_fmac_f32_e32 v213, v230, v230
	v_fmac_f32_e32 v213, v231, v231
	v_lshlrev_b32_e32 v230, 16, v203
	v_and_b32_e32 v231, 0xffff0000, v203
	v_fmac_f32_e32 v213, v230, v230
	v_fmac_f32_e32 v213, v231, v231
	v_lshlrev_b32_e32 v230, 16, v204
	v_and_b32_e32 v231, 0xffff0000, v204
	v_fmac_f32_e32 v213, v230, v230
	v_fmac_f32_e32 v213, v231, v231
	v_lshlrev_b32_e32 v230, 16, v205
	v_and_b32_e32 v231, 0xffff0000, v205
	v_fmac_f32_e32 v213, v230, v230
	v_fmac_f32_e32 v213, v231, v231
	v_lshlrev_b32_e32 v230, 16, v206
	v_and_b32_e32 v231, 0xffff0000, v206
	v_fmac_f32_e32 v213, v230, v230
	v_fmac_f32_e32 v213, v231, v231
	v_lshlrev_b32_e32 v230, 16, v207
	v_and_b32_e32 v231, 0xffff0000, v207
	v_fmac_f32_e32 v213, v230, v230
	v_fmac_f32_e32 v213, v231, v231
	v_lshlrev_b32_e32 v230, 16, v208
	v_and_b32_e32 v231, 0xffff0000, v208
	v_fmac_f32_e32 v213, v230, v230
	v_fmac_f32_e32 v213, v231, v231
	v_lshlrev_b32_e32 v230, 16, v209
	v_and_b32_e32 v231, 0xffff0000, v209
	v_fmac_f32_e32 v213, v230, v230
	v_fmac_f32_e32 v213, v231, v231
	v_lshlrev_b32_e32 v230, 16, v210
	v_and_b32_e32 v231, 0xffff0000, v210
	v_fmac_f32_e32 v213, v230, v230
	v_fmac_f32_e32 v213, v231, v231
	v_lshlrev_b32_e32 v230, 16, v211
	v_and_b32_e32 v231, 0xffff0000, v211
	v_fmac_f32_e32 v213, v230, v230
	v_fmac_f32_e32 v213, v231, v231
	v_mov_b32_e32 v230, v213
	s_nop 1
	v_permlane32_swap_b32_e32 v213, v230
	s_nop 0
	v_add_f32_e32 v213, v213, v230
	s_lshl_b64 s[4:5], s[66:67], 5
	s_add_u32 s4, s4, s82
	s_addc_u32 s5, s5, s83
	s_lshl_b32 s53, s68, 2
	s_add_u32 s4, s4, s53
	s_addc_u32 s5, s5, 0
	v_lshlrev_b32_e32 v235, 5, v140
	v_cmp_gt_u32_e32 vcc, 32, v139
	s_and_saveexec_b64 s[46:47], vcc
	global_store_dword v235, v213, s[4:5]
	s_or_b64 exec, exec, s[46:47]
	s_mov_b32 m0, s54
	s_lshl_b32 s48, s68, 7
	s_xor_b64 s[46:47], s[70:71], -1
	s_branch .LBB0_915
.Lat_u1x_rare:
	s_nop 15
	v_mov_b32_e32 v131, v129
	s_nop 1
	v_permlane32_swap_b32_e32 v129, v131
	s_nop 0
	v_max_f32_e32 v129, v129, v131
	v_max_f32_e32 v131, 0, v129
	v_exp_f32_e64 v147, -v131
	v_add_f32_e32 v130, v130, v131
	s_nop 0
	v_mul_f32_e32 v128, v128, v147
	v_sub_f32_e32 v104, v104, v131
	v_sub_f32_e32 v105, v105, v131
	v_sub_f32_e32 v106, v106, v131
	v_sub_f32_e32 v107, v107, v131
	v_sub_f32_e32 v108, v108, v131
	v_sub_f32_e32 v109, v109, v131
	v_sub_f32_e32 v110, v110, v131
	v_sub_f32_e32 v111, v111, v131
	v_sub_f32_e32 v112, v112, v131
	v_sub_f32_e32 v113, v113, v131
	v_sub_f32_e32 v114, v114, v131
	v_sub_f32_e32 v115, v115, v131
	v_sub_f32_e32 v116, v116, v131
	v_sub_f32_e32 v117, v117, v131
	v_sub_f32_e32 v118, v118, v131
	v_sub_f32_e32 v119, v119, v131
	v_sub_f32_e32 v238, v238, v131
	v_sub_f32_e32 v239, v239, v131
	v_sub_f32_e32 v240, v240, v131
	v_sub_f32_e32 v241, v241, v131
	v_sub_f32_e32 v242, v242, v131
	v_sub_f32_e32 v243, v243, v131
	v_sub_f32_e32 v244, v244, v131
	v_sub_f32_e32 v245, v245, v131
	v_sub_f32_e32 v246, v246, v131
	v_sub_f32_e32 v247, v247, v131
	v_sub_f32_e32 v248, v248, v131
	v_sub_f32_e32 v249, v249, v131
	v_sub_f32_e32 v250, v250, v131
	v_sub_f32_e32 v251, v251, v131
	v_sub_f32_e32 v252, v252, v131
	v_sub_f32_e32 v253, v253, v131
	v_sub_f32_e32 v180, v180, v131
	v_sub_f32_e32 v181, v181, v131
	v_sub_f32_e32 v182, v182, v131
	v_sub_f32_e32 v183, v183, v131
	v_sub_f32_e32 v184, v184, v131
	v_sub_f32_e32 v185, v185, v131
	v_sub_f32_e32 v186, v186, v131
	v_sub_f32_e32 v187, v187, v131
	v_sub_f32_e32 v188, v188, v131
	v_sub_f32_e32 v189, v189, v131
	v_sub_f32_e32 v190, v190, v131
	v_sub_f32_e32 v191, v191, v131
	v_sub_f32_e32 v192, v192, v131
	v_sub_f32_e32 v193, v193, v131
	v_sub_f32_e32 v194, v194, v131
	v_sub_f32_e32 v195, v195, v131
	v_mul_f32_e32 v16, v16, v147
	v_mul_f32_e32 v32, v32, v147
	v_mul_f32_e32 v17, v17, v147
	v_mul_f32_e32 v33, v33, v147
	v_mul_f32_e32 v18, v18, v147
	v_mul_f32_e32 v34, v34, v147
	v_mul_f32_e32 v19, v19, v147
	v_mul_f32_e32 v35, v35, v147
	v_mul_f32_e32 v20, v20, v147
	v_mul_f32_e32 v36, v36, v147
	v_mul_f32_e32 v21, v21, v147
	v_mul_f32_e32 v37, v37, v147
	v_mul_f32_e32 v22, v22, v147
	v_mul_f32_e32 v38, v38, v147
	v_mul_f32_e32 v23, v23, v147
	v_mul_f32_e32 v39, v39, v147
	v_mul_f32_e32 v24, v24, v147
	v_mul_f32_e32 v40, v40, v147
	v_mul_f32_e32 v25, v25, v147
	v_mul_f32_e32 v41, v41, v147
	v_mul_f32_e32 v26, v26, v147
	v_mul_f32_e32 v42, v42, v147
	v_mul_f32_e32 v27, v27, v147
	v_mul_f32_e32 v43, v43, v147
	v_mul_f32_e32 v28, v28, v147
	v_mul_f32_e32 v44, v44, v147
	v_mul_f32_e32 v29, v29, v147
	v_mul_f32_e32 v45, v45, v147
	v_mul_f32_e32 v30, v30, v147
	v_mul_f32_e32 v46, v46, v147
	v_mul_f32_e32 v31, v31, v147
	v_mul_f32_e32 v47, v47, v147
	s_branch .Lat_u1x_back
.Lat_u1y_rare:
	s_nop 15
	v_mov_b32_e32 v131, v129
	s_nop 1
	v_permlane32_swap_b32_e32 v129, v131
	s_nop 0
	v_max_f32_e32 v129, v129, v131
	v_max_f32_e32 v131, 0, v129
	v_exp_f32_e64 v147, -v131
	v_add_f32_e32 v130, v130, v131
	s_nop 0
	v_mul_f32_e32 v128, v128, v147
	v_sub_f32_e32 v104, v104, v131
	v_sub_f32_e32 v105, v105, v131
	v_sub_f32_e32 v106, v106, v131
	v_sub_f32_e32 v107, v107, v131
	v_sub_f32_e32 v108, v108, v131
	v_sub_f32_e32 v109, v109, v131
	v_sub_f32_e32 v110, v110, v131
	v_sub_f32_e32 v111, v111, v131
	v_sub_f32_e32 v112, v112, v131
	v_sub_f32_e32 v113, v113, v131
	v_sub_f32_e32 v114, v114, v131
	v_sub_f32_e32 v115, v115, v131
	v_sub_f32_e32 v116, v116, v131
	v_sub_f32_e32 v117, v117, v131
	v_sub_f32_e32 v118, v118, v131
	v_sub_f32_e32 v119, v119, v131
	v_sub_f32_e32 v64, v64, v131
	v_sub_f32_e32 v65, v65, v131
	v_sub_f32_e32 v66, v66, v131
	v_sub_f32_e32 v67, v67, v131
	v_sub_f32_e32 v68, v68, v131
	v_sub_f32_e32 v69, v69, v131
	v_sub_f32_e32 v70, v70, v131
	v_sub_f32_e32 v71, v71, v131
	v_sub_f32_e32 v72, v72, v131
	v_sub_f32_e32 v73, v73, v131
	v_sub_f32_e32 v74, v74, v131
	v_sub_f32_e32 v75, v75, v131
	v_sub_f32_e32 v76, v76, v131
	v_sub_f32_e32 v77, v77, v131
	v_sub_f32_e32 v78, v78, v131
	v_sub_f32_e32 v79, v79, v131
	v_sub_f32_e32 v48, v48, v131
	v_sub_f32_e32 v49, v49, v131
	v_sub_f32_e32 v50, v50, v131
	v_sub_f32_e32 v51, v51, v131
	v_sub_f32_e32 v52, v52, v131
	v_sub_f32_e32 v53, v53, v131
	v_sub_f32_e32 v54, v54, v131
	v_sub_f32_e32 v55, v55, v131
	v_sub_f32_e32 v56, v56, v131
	v_sub_f32_e32 v57, v57, v131
	v_sub_f32_e32 v58, v58, v131
	v_sub_f32_e32 v59, v59, v131
	v_sub_f32_e32 v60, v60, v131
	v_sub_f32_e32 v61, v61, v131
	v_sub_f32_e32 v62, v62, v131
	v_sub_f32_e32 v63, v63, v131
	v_mul_f32_e32 v16, v16, v147
	v_mul_f32_e32 v32, v32, v147
	v_mul_f32_e32 v17, v17, v147
	v_mul_f32_e32 v33, v33, v147
	v_mul_f32_e32 v18, v18, v147
	v_mul_f32_e32 v34, v34, v147
	v_mul_f32_e32 v19, v19, v147
	v_mul_f32_e32 v35, v35, v147
	v_mul_f32_e32 v20, v20, v147
	v_mul_f32_e32 v36, v36, v147
	v_mul_f32_e32 v21, v21, v147
	v_mul_f32_e32 v37, v37, v147
	v_mul_f32_e32 v22, v22, v147
	v_mul_f32_e32 v38, v38, v147
	v_mul_f32_e32 v23, v23, v147
	v_mul_f32_e32 v39, v39, v147
	v_mul_f32_e32 v24, v24, v147
	v_mul_f32_e32 v40, v40, v147
	v_mul_f32_e32 v25, v25, v147
	v_mul_f32_e32 v41, v41, v147
	v_mul_f32_e32 v26, v26, v147
	v_mul_f32_e32 v42, v42, v147
	v_mul_f32_e32 v27, v27, v147
	v_mul_f32_e32 v43, v43, v147
	v_mul_f32_e32 v28, v28, v147
	v_mul_f32_e32 v44, v44, v147
	v_mul_f32_e32 v29, v29, v147
	v_mul_f32_e32 v45, v45, v147
	v_mul_f32_e32 v30, v30, v147
	v_mul_f32_e32 v46, v46, v147
	v_mul_f32_e32 v31, v31, v147
	v_mul_f32_e32 v47, v47, v147
	s_branch .Lat_u1y_back
.Lat_u1x_noqk:
	s_lshr_b32 s4, s69, 1
	s_sub_u32 s4, s52, s4
	s_sub_u32 s4, s4, 1
	s_cmp_gt_i32 s4, s87
	s_cbranch_scc1 .Lat_u1x_idle
	s_lshl_b32 s4, s50, 13
	s_add_i32 s4, s4, 0x6000
	s_and_b32 s4, s4, 0x6000
	v_add_u32_e32 v159, s4, v144
	ds_read_b64_tr_b16 v[196:197], v159 offset:36864
	ds_read_b64_tr_b16 v[198:199], v159 offset:37376
	ds_read_b64_tr_b16 v[200:201], v159 offset:37888
	ds_read_b64_tr_b16 v[202:203], v159 offset:38400
	ds_read_b64_tr_b16 v[204:205], v159 offset:38912
	ds_read_b64_tr_b16 v[206:207], v159 offset:39424
	ds_read_b64_tr_b16 v[208:209], v159 offset:39936
	ds_read_b64_tr_b16 v[210:211], v159 offset:40448
	ds_read_b64_tr_b16 v[212:213], v159 offset:40960
	ds_read_b64_tr_b16 v[214:215], v159 offset:41472
	ds_read_b64_tr_b16 v[230:231], v159 offset:41984
	ds_read_b64_tr_b16 v[232:233], v159 offset:42496
	ds_read_b64_tr_b16 v[234:235], v159 offset:43008
	ds_read_b64_tr_b16 v[236:237], v159 offset:43520
	ds_read_b64_tr_b16 v[164:165], v159 offset:44032
	ds_read_b64_tr_b16 v[166:167], v159 offset:44544
	v_mov_b32_e32 v156, 0
	v_mov_b32_e32 v157, 0
	v_exp_f32_e32 v64, v64
	v_exp_f32_e32 v65, v65
	v_add_f32_e32 v156, v156, v64
	v_add_f32_e32 v156, v156, v65
	v_cvt_pk_bf16_f32 v64, v64, v65
	v_exp_f32_e32 v66, v66
	v_exp_f32_e32 v67, v67
	v_add_f32_e32 v157, v157, v66
	v_add_f32_e32 v157, v157, v67
	v_cvt_pk_bf16_f32 v65, v66, v67
	v_exp_f32_e32 v68, v68
	v_exp_f32_e32 v69, v69
	v_add_f32_e32 v156, v156, v68
	v_add_f32_e32 v156, v156, v69
	v_cvt_pk_bf16_f32 v66, v68, v69
	v_exp_f32_e32 v70, v70
	v_exp_f32_e32 v71, v71
	v_add_f32_e32 v157, v157, v70
	v_add_f32_e32 v157, v157, v71
	v_cvt_pk_bf16_f32 v67, v70, v71
	v_exp_f32_e32 v72, v72
	v_exp_f32_e32 v73, v73
	v_add_f32_e32 v156, v156, v72
	v_add_f32_e32 v156, v156, v73
	v_cvt_pk_bf16_f32 v68, v72, v73
	v_exp_f32_e32 v74, v74
	v_exp_f32_e32 v75, v75
	v_add_f32_e32 v157, v157, v74
	v_add_f32_e32 v157, v157, v75
	v_cvt_pk_bf16_f32 v69, v74, v75
	v_exp_f32_e32 v76, v76
	v_exp_f32_e32 v77, v77
	v_add_f32_e32 v156, v156, v76
	v_add_f32_e32 v156, v156, v77
	v_cvt_pk_bf16_f32 v70, v76, v77
	v_exp_f32_e32 v78, v78
	v_exp_f32_e32 v79, v79
	v_add_f32_e32 v157, v157, v78
	v_add_f32_e32 v157, v157, v79
	v_cvt_pk_bf16_f32 v71, v78, v79
	s_nop 1
	s_waitcnt lgkmcnt(0)
	v_mfma_f32_32x32x16_bf16 v[16:31], v[196:199], v[64:67], v[16:31]
	v_exp_f32_e32 v48, v48
	v_exp_f32_e32 v49, v49
	v_add_f32_e32 v156, v156, v48
	v_add_f32_e32 v156, v156, v49
	v_cvt_pk_bf16_f32 v48, v48, v49
	v_exp_f32_e32 v50, v50
	v_exp_f32_e32 v51, v51
	v_add_f32_e32 v157, v157, v50
	v_add_f32_e32 v157, v157, v51
	v_cvt_pk_bf16_f32 v49, v50, v51
	v_mfma_f32_32x32x16_bf16 v[32:47], v[212:215], v[64:67], v[32:47]
	v_exp_f32_e32 v52, v52
	v_exp_f32_e32 v53, v53
	v_add_f32_e32 v156, v156, v52
	v_add_f32_e32 v156, v156, v53
	v_cvt_pk_bf16_f32 v50, v52, v53
	v_exp_f32_e32 v54, v54
	v_exp_f32_e32 v55, v55
	v_add_f32_e32 v157, v157, v54
	v_add_f32_e32 v157, v157, v55
	v_cvt_pk_bf16_f32 v51, v54, v55
	v_mfma_f32_32x32x16_bf16 v[16:31], v[200:203], v[68:71], v[16:31]
	v_exp_f32_e32 v56, v56
	v_exp_f32_e32 v57, v57
	v_add_f32_e32 v156, v156, v56
	v_add_f32_e32 v156, v156, v57
	v_cvt_pk_bf16_f32 v52, v56, v57
	v_exp_f32_e32 v58, v58
	v_exp_f32_e32 v59, v59
	v_add_f32_e32 v157, v157, v58
	v_add_f32_e32 v157, v157, v59
	v_cvt_pk_bf16_f32 v53, v58, v59
	v_mfma_f32_32x32x16_bf16 v[32:47], v[230:233], v[68:71], v[32:47]
	v_exp_f32_e32 v60, v60
	v_exp_f32_e32 v61, v61
	v_add_f32_e32 v156, v156, v60
	v_add_f32_e32 v156, v156, v61
	v_cvt_pk_bf16_f32 v54, v60, v61
	v_exp_f32_e32 v62, v62
	v_exp_f32_e32 v63, v63
	v_add_f32_e32 v157, v157, v62
	v_add_f32_e32 v157, v157, v63
	v_cvt_pk_bf16_f32 v55, v62, v63
	s_nop 1
	v_mfma_f32_32x32x16_bf16 v[16:31], v[204:207], v[48:51], v[16:31]
	v_mfma_f32_32x32x16_bf16 v[32:47], v[234:237], v[48:51], v[32:47]
	v_mfma_f32_32x32x16_bf16 v[16:31], v[208:211], v[52:55], v[16:31]
	v_mfma_f32_32x32x16_bf16 v[32:47], v[164:167], v[52:55], v[32:47]
	v_add_f32_e32 v156, v156, v157
	v_add_f32_e32 v128, v128, v156

.Lat_u1y_noqk:
	s_lshr_b32 s4, s69, 1
	s_sub_u32 s4, s52, s4
	s_sub_u32 s4, s4, 1
	s_cmp_gt_i32 s4, s87
	s_cbranch_scc1 .Lat_u1y_idle
	s_lshl_b32 s4, s50, 13
	s_add_i32 s4, s4, 0x6000
	s_and_b32 s4, s4, 0x6000
	v_add_u32_e32 v159, s4, v144
	ds_read_b64_tr_b16 v[196:197], v159 offset:36864
	ds_read_b64_tr_b16 v[198:199], v159 offset:37376
	ds_read_b64_tr_b16 v[200:201], v159 offset:37888
	ds_read_b64_tr_b16 v[202:203], v159 offset:38400
	ds_read_b64_tr_b16 v[204:205], v159 offset:38912
	ds_read_b64_tr_b16 v[206:207], v159 offset:39424
	ds_read_b64_tr_b16 v[208:209], v159 offset:39936
	ds_read_b64_tr_b16 v[210:211], v159 offset:40448
	ds_read_b64_tr_b16 v[212:213], v159 offset:40960
	ds_read_b64_tr_b16 v[214:215], v159 offset:41472
	ds_read_b64_tr_b16 v[230:231], v159 offset:41984
	ds_read_b64_tr_b16 v[232:233], v159 offset:42496
	ds_read_b64_tr_b16 v[234:235], v159 offset:43008
	ds_read_b64_tr_b16 v[236:237], v159 offset:43520
	ds_read_b64_tr_b16 v[164:165], v159 offset:44032
	ds_read_b64_tr_b16 v[166:167], v159 offset:44544
	v_mov_b32_e32 v156, 0
	v_mov_b32_e32 v157, 0
	v_exp_f32_e32 v238, v238
	v_exp_f32_e32 v239, v239
	v_add_f32_e32 v156, v156, v238
	v_add_f32_e32 v156, v156, v239
	v_cvt_pk_bf16_f32 v238, v238, v239
	v_exp_f32_e32 v240, v240
	v_exp_f32_e32 v241, v241
	v_add_f32_e32 v157, v157, v240
	v_add_f32_e32 v157, v157, v241
	v_cvt_pk_bf16_f32 v239, v240, v241
	v_exp_f32_e32 v242, v242
	v_exp_f32_e32 v243, v243
	v_add_f32_e32 v156, v156, v242
	v_add_f32_e32 v156, v156, v243
	v_cvt_pk_bf16_f32 v240, v242, v243
	v_exp_f32_e32 v244, v244
	v_exp_f32_e32 v245, v245
	v_add_f32_e32 v157, v157, v244
	v_add_f32_e32 v157, v157, v245
	v_cvt_pk_bf16_f32 v241, v244, v245
	v_exp_f32_e32 v246, v246
	v_exp_f32_e32 v247, v247
	v_add_f32_e32 v156, v156, v246
	v_add_f32_e32 v156, v156, v247
	v_cvt_pk_bf16_f32 v242, v246, v247
	v_exp_f32_e32 v248, v248
	v_exp_f32_e32 v249, v249
	v_add_f32_e32 v157, v157, v248
	v_add_f32_e32 v157, v157, v249
	v_cvt_pk_bf16_f32 v243, v248, v249
	v_exp_f32_e32 v250, v250
	v_exp_f32_e32 v251, v251
	v_add_f32_e32 v156, v156, v250
	v_add_f32_e32 v156, v156, v251
	v_cvt_pk_bf16_f32 v244, v250, v251
	v_exp_f32_e32 v252, v252
	v_exp_f32_e32 v253, v253
	v_add_f32_e32 v157, v157, v252
	v_add_f32_e32 v157, v157, v253
	v_cvt_pk_bf16_f32 v245, v252, v253
	s_nop 1
	s_waitcnt lgkmcnt(0)
	v_mfma_f32_32x32x16_bf16 v[16:31], v[196:199], v[238:241], v[16:31]
	v_exp_f32_e32 v180, v180
	v_exp_f32_e32 v181, v181
	v_add_f32_e32 v156, v156, v180
	v_add_f32_e32 v156, v156, v181
	v_cvt_pk_bf16_f32 v180, v180, v181
	v_exp_f32_e32 v182, v182
	v_exp_f32_e32 v183, v183
	v_add_f32_e32 v157, v157, v182
	v_add_f32_e32 v157, v157, v183
	v_cvt_pk_bf16_f32 v181, v182, v183
	v_mfma_f32_32x32x16_bf16 v[32:47], v[212:215], v[238:241], v[32:47]
	v_exp_f32_e32 v184, v184
	v_exp_f32_e32 v185, v185
	v_add_f32_e32 v156, v156, v184
	v_add_f32_e32 v156, v156, v185
	v_cvt_pk_bf16_f32 v182, v184, v185
	v_exp_f32_e32 v186, v186
	v_exp_f32_e32 v187, v187
	v_add_f32_e32 v157, v157, v186
	v_add_f32_e32 v157, v157, v187
	v_cvt_pk_bf16_f32 v183, v186, v187
	v_mfma_f32_32x32x16_bf16 v[16:31], v[200:203], v[242:245], v[16:31]
	v_exp_f32_e32 v188, v188
	v_exp_f32_e32 v189, v189
	v_add_f32_e32 v156, v156, v188
	v_add_f32_e32 v156, v156, v189
	v_cvt_pk_bf16_f32 v184, v188, v189
	v_exp_f32_e32 v190, v190
	v_exp_f32_e32 v191, v191
	v_add_f32_e32 v157, v157, v190
	v_add_f32_e32 v157, v157, v191
	v_cvt_pk_bf16_f32 v185, v190, v191
	v_mfma_f32_32x32x16_bf16 v[32:47], v[230:233], v[242:245], v[32:47]
	v_exp_f32_e32 v192, v192
	v_exp_f32_e32 v193, v193
	v_add_f32_e32 v156, v156, v192
	v_add_f32_e32 v156, v156, v193
	v_cvt_pk_bf16_f32 v186, v192, v193
	v_exp_f32_e32 v194, v194
	v_exp_f32_e32 v195, v195
	v_add_f32_e32 v157, v157, v194
	v_add_f32_e32 v157, v157, v195
	v_cvt_pk_bf16_f32 v187, v194, v195
	s_nop 1
	v_mfma_f32_32x32x16_bf16 v[16:31], v[204:207], v[180:183], v[16:31]
	v_mfma_f32_32x32x16_bf16 v[32:47], v[234:237], v[180:183], v[32:47]
	v_mfma_f32_32x32x16_bf16 v[16:31], v[208:211], v[184:187], v[16:31]
	v_mfma_f32_32x32x16_bf16 v[32:47], v[164:167], v[184:187], v[32:47]
	v_add_f32_e32 v156, v156, v157
	v_add_f32_e32 v128, v128, v156

.Lat_u2x_bar:
	s_barrier
	s_lshr_b32 s4, s56, 1
	s_sub_u32 s4, s62, s4
	s_cmp_gt_i32 s4, s91
	s_cbranch_scc1 .Lat_u2x_noqk
	s_mul_i32 s63, s61, 0x3000
	v_add_u32_e32 v158, s63, v146
	ds_read_b128 v[196:199], v158
	ds_read_b128 v[200:203], v158 offset:512
	ds_read_b128 v[204:207], v158 offset:2048
	ds_read_b128 v[208:211], v158 offset:2560
	ds_read_b128 v[212:215], v158 offset:4096
	ds_read_b128 v[230:233], v158 offset:4608
	ds_read_b128 v[234:237], v158 offset:6144
	ds_read_b128 v[164:167], v158 offset:6656
	ds_read_b128 v[168:171], v158 offset:8192
	ds_read_b128 v[172:175], v158 offset:8704
	ds_read_b128 v[148:151], v158 offset:10240
	ds_read_b128 v[152:155], v158 offset:10752
	s_lshl_b32 s4, s64, 13
	s_add_i32 s4, s4, 0x6000
	s_and_b32 s4, s4, 0x6000
	v_add_u32_e32 v159, s4, v143
	v_mov_b32_e32 v156, 0
	v_mov_b32_e32 v157, 0
	s_waitcnt lgkmcnt(11)
	v_mfma_f32_32x32x16_bf16 v[238:253], v[196:199], v[86:89], v[104:119]
	ds_read_b64_tr_b16 v[196:197], v159 offset:36864
	ds_read_b64_tr_b16 v[198:199], v159 offset:37376
	v_exp_f32_e32 v50, v50
	v_exp_f32_e32 v51, v51
	v_add_f32_e32 v156, v156, v50
	v_add_f32_e32 v156, v156, v51
	v_cvt_pk_bf16_f32 v50, v50, v51
	s_waitcnt lgkmcnt(12)
	v_mfma_f32_32x32x16_bf16 v[180:195], v[200:203], v[86:89], v[104:119]
	ds_read_b64_tr_b16 v[200:201], v159 offset:37888
	ds_read_b64_tr_b16 v[202:203], v159 offset:38400
	v_exp_f32_e32 v52, v52
	v_exp_f32_e32 v53, v53
	v_add_f32_e32 v157, v157, v52
	v_add_f32_e32 v157, v157, v53
	v_cvt_pk_bf16_f32 v51, v52, v53
	s_waitcnt lgkmcnt(13)
	v_mfma_f32_32x32x16_bf16 v[238:253], v[204:207], v[82:85], v[238:253]
	ds_read_b64_tr_b16 v[204:205], v159 offset:38912
	ds_read_b64_tr_b16 v[206:207], v159 offset:39424
	v_exp_f32_e32 v54, v54
	v_exp_f32_e32 v55, v55
	v_add_f32_e32 v156, v156, v54
	v_add_f32_e32 v156, v156, v55
	v_cvt_pk_bf16_f32 v52, v54, v55
	s_waitcnt lgkmcnt(14)
	v_mfma_f32_32x32x16_bf16 v[180:195], v[208:211], v[82:85], v[180:195]
	ds_read_b64_tr_b16 v[208:209], v159 offset:39936
	ds_read_b64_tr_b16 v[210:211], v159 offset:40448
	v_exp_f32_e32 v56, v56
	v_exp_f32_e32 v57, v57
	v_add_f32_e32 v157, v157, v56
	v_add_f32_e32 v157, v157, v57
	v_cvt_pk_bf16_f32 v53, v56, v57
	s_waitcnt lgkmcnt(15)
	v_mfma_f32_32x32x16_bf16 v[238:253], v[212:215], v[78:81], v[238:253]
	ds_read_b64_tr_b16 v[212:213], v159 offset:40960
	ds_read_b64_tr_b16 v[214:215], v159 offset:41472
	v_exp_f32_e32 v58, v58
	v_exp_f32_e32 v59, v59
	v_add_f32_e32 v156, v156, v58
	v_add_f32_e32 v156, v156, v59
	v_cvt_pk_bf16_f32 v54, v58, v59
	s_waitcnt lgkmcnt(15)
	v_mfma_f32_32x32x16_bf16 v[180:195], v[230:233], v[78:81], v[180:195]
	ds_read_b64_tr_b16 v[230:231], v159 offset:41984
	ds_read_b64_tr_b16 v[232:233], v159 offset:42496
	v_exp_f32_e32 v60, v60
	v_exp_f32_e32 v61, v61
	v_add_f32_e32 v157, v157, v60
	v_add_f32_e32 v157, v157, v61
	v_cvt_pk_bf16_f32 v55, v60, v61
	s_waitcnt lgkmcnt(15)
	v_mfma_f32_32x32x16_bf16 v[238:253], v[234:237], v[74:77], v[238:253]
	ds_read_b64_tr_b16 v[234:235], v159 offset:43008
	ds_read_b64_tr_b16 v[236:237], v159 offset:43520
	v_exp_f32_e32 v62, v62
	v_exp_f32_e32 v63, v63
	v_add_f32_e32 v156, v156, v62
	v_add_f32_e32 v156, v156, v63
	v_cvt_pk_bf16_f32 v56, v62, v63
	s_waitcnt lgkmcnt(15)
	v_mfma_f32_32x32x16_bf16 v[180:195], v[164:167], v[74:77], v[180:195]
	ds_read_b64_tr_b16 v[164:165], v159 offset:44032
	ds_read_b64_tr_b16 v[166:167], v159 offset:44544
	v_exp_f32_e32 v64, v64
	v_exp_f32_e32 v65, v65
	v_add_f32_e32 v157, v157, v64
	v_add_f32_e32 v157, v157, v65
	v_cvt_pk_bf16_f32 v57, v64, v65
	s_waitcnt lgkmcnt(15)
	v_mfma_f32_32x32x16_bf16 v[238:253], v[168:171], v[70:73], v[238:253]
	v_exp_f32_e32 v34, v34
	v_exp_f32_e32 v35, v35
	v_add_f32_e32 v156, v156, v34
	v_add_f32_e32 v156, v156, v35
	v_cvt_pk_bf16_f32 v34, v34, v35
	s_waitcnt lgkmcnt(15)
	v_mfma_f32_32x32x16_bf16 v[180:195], v[172:175], v[70:73], v[180:195]
	v_exp_f32_e32 v36, v36
	v_exp_f32_e32 v37, v37
	v_add_f32_e32 v157, v157, v36
	v_add_f32_e32 v157, v157, v37
	v_cvt_pk_bf16_f32 v35, v36, v37
	s_waitcnt lgkmcnt(15)
	v_mfma_f32_32x32x16_bf16 v[238:253], v[148:151], v[66:69], v[238:253]
	v_exp_f32_e32 v38, v38
	v_exp_f32_e32 v39, v39
	v_add_f32_e32 v156, v156, v38
	v_add_f32_e32 v156, v156, v39
	v_cvt_pk_bf16_f32 v36, v38, v39
	s_waitcnt lgkmcnt(15)
	v_mfma_f32_32x32x16_bf16 v[180:195], v[152:155], v[66:69], v[180:195]
	v_exp_f32_e32 v40, v40
	v_exp_f32_e32 v41, v41
	v_add_f32_e32 v157, v157, v40
	v_add_f32_e32 v157, v157, v41
	v_cvt_pk_bf16_f32 v37, v40, v41
	s_nop 1
	s_waitcnt lgkmcnt(0)
	v_mfma_f32_32x32x16_bf16 v[18:33], v[196:199], v[50:53], v[18:33]
	v_exp_f32_e32 v42, v42
	v_exp_f32_e32 v43, v43
	v_add_f32_e32 v156, v156, v42
	v_add_f32_e32 v156, v156, v43
	v_cvt_pk_bf16_f32 v38, v42, v43
	s_nop 1
	v_mfma_f32_32x32x16_bf16 v[2:17], v[212:215], v[50:53], v[2:17]
	s_mul_i32 s63, s61, 0x3000
	s_add_i32 s4, s62, 2
	s_cmp_ge_u32 s4, s90
	s_cbranch_scc1 .Lat_u2x_nodma
	s_add_i32 s4, s63, 0xffffd000
	s_cmp_lg_u32 s61, 0
	s_cselect_b32 s4, s4, 0x6000
	s_add_i32 s5, s4, s58
	s_mov_b32 m0, s5
	s_add_i32 s4, s4, s59
	global_load_lds_dwordx4 v[126:127], off
	s_mov_b32 m0, s4
	s_cmp_lt_u32 s56, 4
	s_cbranch_scc0 .Lat_u2x_nok2
	global_load_lds_dwordx4 v[122:123], off

; __device__ __forceinline__ void cmask(f32x16& p0, f32x16& p1, int jb, int qrel, int hi) {
;     const float NEG = -INFINITY; const int kb = 64 * jb + 4 * hi;
; #pragma unroll
;     for (int r = 0; r < 16; ++r) { const int kv = kb + (r & 3) + 8 * (r >> 2); if (kv > qrel) p0[r] = NEG; if (kv + 32 > qrel) p1[r] = NEG; }
; }
.Lat_u2x_nodma:
	v_lshl_add_u64 v[126:127], v[126:127], 0, s[34:35]
	v_lshl_add_u64 v[122:123], v[122:123], 0, s[20:21]
	v_lshl_add_u64 v[124:125], v[124:125], 0, s[34:35]
	v_exp_f32_e32 v44, v44
	v_exp_f32_e32 v45, v45
	v_add_f32_e32 v157, v157, v44
	v_add_f32_e32 v157, v157, v45
	v_cvt_pk_bf16_f32 v39, v44, v45
	s_nop 1
	v_mfma_f32_32x32x16_bf16 v[18:33], v[200:203], v[54:57], v[18:33]
	v_exp_f32_e32 v46, v46
	v_exp_f32_e32 v47, v47
	v_add_f32_e32 v156, v156, v46
	v_add_f32_e32 v156, v156, v47
	v_cvt_pk_bf16_f32 v40, v46, v47
	s_nop 1
	v_mfma_f32_32x32x16_bf16 v[2:17], v[230:233], v[54:57], v[2:17]
	v_exp_f32_e32 v48, v48
	v_exp_f32_e32 v49, v49
	v_add_f32_e32 v157, v157, v48
	v_add_f32_e32 v157, v157, v49
	v_cvt_pk_bf16_f32 v41, v48, v49
	s_nop 1
	v_mfma_f32_32x32x16_bf16 v[18:33], v[204:207], v[34:37], v[18:33]
	v_mfma_f32_32x32x16_bf16 v[2:17], v[234:237], v[34:37], v[2:17]
	v_mfma_f32_32x32x16_bf16 v[18:33], v[208:211], v[38:41], v[18:33]
	v_mfma_f32_32x32x16_bf16 v[2:17], v[164:167], v[38:41], v[2:17]
	v_add_f32_e32 v156, v156, v157
	v_add_f32_e32 v128, v128, v156
	s_cmp_lt_u32 s62, s91
	s_cbranch_scc1 .Lat_u2x_nomask
	s_sub_i32 s4, s62, s91
	s_lshl_b32 s4, s4, 6
	s_nop 7
	s_nop 7
	v_lshl_add_u32 v133, v142, 2, s4
	v_sub_u32_e32 v133, v145, v133
	v_cmp_gt_i32_e32 vcc, 0, v133
	s_nop 1
	v_cndmask_b32_e32 v238, v238, v220, vcc
	v_cmp_gt_i32_e32 vcc, 1, v133
	s_nop 1
	v_cndmask_b32_e32 v239, v239, v220, vcc
	v_cmp_gt_i32_e32 vcc, 2, v133
	s_nop 1
	v_cndmask_b32_e32 v240, v240, v220, vcc
	v_cmp_gt_i32_e32 vcc, 3, v133
	s_nop 1
	v_cndmask_b32_e32 v241, v241, v220, vcc
	v_cmp_gt_i32_e32 vcc, 8, v133
	s_nop 1
	v_cndmask_b32_e32 v242, v242, v220, vcc
	v_cmp_gt_i32_e32 vcc, 9, v133
	s_nop 1
	v_cndmask_b32_e32 v243, v243, v220, vcc
	v_cmp_gt_i32_e32 vcc, 10, v133
	s_nop 1
	v_cndmask_b32_e32 v244, v244, v220, vcc
	v_cmp_gt_i32_e32 vcc, 11, v133
	s_nop 1
	v_cndmask_b32_e32 v245, v245, v220, vcc
	v_cmp_gt_i32_e32 vcc, 16, v133
	s_nop 1
	v_cndmask_b32_e32 v246, v246, v220, vcc
	v_cmp_gt_i32_e32 vcc, 17, v133
	s_nop 1
	v_cndmask_b32_e32 v247, v247, v220, vcc
	v_cmp_gt_i32_e32 vcc, 18, v133
	s_nop 1
	v_cndmask_b32_e32 v248, v248, v220, vcc
	v_cmp_gt_i32_e32 vcc, 19, v133
	s_nop 1
	v_cndmask_b32_e32 v249, v249, v220, vcc
	v_cmp_gt_i32_e32 vcc, 24, v133
	s_nop 1
	v_cndmask_b32_e32 v250, v250, v220, vcc
	v_cmp_gt_i32_e32 vcc, 25, v133
	s_nop 1
	v_cndmask_b32_e32 v251, v251, v220, vcc
	v_cmp_gt_i32_e32 vcc, 26, v133
	s_nop 1
	v_cndmask_b32_e32 v252, v252, v220, vcc
	v_cmp_gt_i32_e32 vcc, 27, v133
	s_nop 1
	v_cndmask_b32_e32 v253, v253, v220, vcc
	v_cmp_gt_i32_e32 vcc, 32, v133
	s_nop 1
	v_cndmask_b32_e32 v180, v180, v220, vcc
	v_cmp_gt_i32_e32 vcc, 33, v133
	s_nop 1
	v_cndmask_b32_e32 v181, v181, v220, vcc
	v_cmp_gt_i32_e32 vcc, 34, v133
	s_nop 1
	v_cndmask_b32_e32 v182, v182, v220, vcc
	v_cmp_gt_i32_e32 vcc, 35, v133
	s_nop 1
	v_cndmask_b32_e32 v183, v183, v220, vcc
	v_cmp_gt_i32_e32 vcc, 40, v133
	s_nop 1
	v_cndmask_b32_e32 v184, v184, v220, vcc
	v_cmp_gt_i32_e32 vcc, 41, v133
	s_nop 1
	v_cndmask_b32_e32 v185, v185, v220, vcc
	v_cmp_gt_i32_e32 vcc, 42, v133
	s_nop 1
	v_cndmask_b32_e32 v186, v186, v220, vcc
	v_cmp_gt_i32_e32 vcc, 43, v133
	s_nop 1
	v_cndmask_b32_e32 v187, v187, v220, vcc
	v_cmp_gt_i32_e32 vcc, 48, v133
	s_nop 1
	v_cndmask_b32_e32 v188, v188, v220, vcc
	v_cmp_gt_i32_e32 vcc, 49, v133
	s_nop 1
	v_cndmask_b32_e32 v189, v189, v220, vcc
	v_cmp_gt_i32_e32 vcc, 50, v133
	s_nop 1
	v_cndmask_b32_e32 v190, v190, v220, vcc
	v_cmp_gt_i32_e32 vcc, 51, v133
	s_nop 1
	v_cndmask_b32_e32 v191, v191, v220, vcc
	v_cmp_gt_i32_e32 vcc, 56, v133
	s_nop 1
	v_cndmask_b32_e32 v192, v192, v220, vcc
	v_cmp_gt_i32_e32 vcc, 57, v133
	s_nop 1
	v_cndmask_b32_e32 v193, v193, v220, vcc
	v_cmp_gt_i32_e32 vcc, 58, v133
	s_nop 1
	v_cndmask_b32_e32 v194, v194, v220, vcc
	v_cmp_gt_i32_e32 vcc, 59, v133
	s_nop 1
	v_cndmask_b32_e32 v195, v195, v220, vcc

.Lat_u2y_bar:
	s_barrier
	s_lshr_b32 s4, s56, 1
	s_sub_u32 s4, s62, s4
	s_cmp_gt_i32 s4, s91
	s_cbranch_scc1 .Lat_u2y_noqk
	s_mul_i32 s63, s61, 0x3000
	v_add_u32_e32 v158, s63, v146
	ds_read_b128 v[196:199], v158
	ds_read_b128 v[200:203], v158 offset:512
	ds_read_b128 v[204:207], v158 offset:2048
	ds_read_b128 v[208:211], v158 offset:2560
	ds_read_b128 v[212:215], v158 offset:4096
	ds_read_b128 v[230:233], v158 offset:4608
	ds_read_b128 v[234:237], v158 offset:6144
	ds_read_b128 v[164:167], v158 offset:6656
	ds_read_b128 v[168:171], v158 offset:8192
	ds_read_b128 v[172:175], v158 offset:8704
	ds_read_b128 v[148:151], v158 offset:10240
	ds_read_b128 v[152:155], v158 offset:10752
	s_lshl_b32 s4, s64, 13
	s_add_i32 s4, s4, 0x6000
	s_and_b32 s4, s4, 0x6000
	v_add_u32_e32 v159, s4, v143
	v_mov_b32_e32 v156, 0
	v_mov_b32_e32 v157, 0
	s_waitcnt lgkmcnt(11)
	v_mfma_f32_32x32x16_bf16 v[50:65], v[196:199], v[86:89], v[104:119]
	ds_read_b64_tr_b16 v[196:197], v159 offset:36864
	ds_read_b64_tr_b16 v[198:199], v159 offset:37376
	v_exp_f32_e32 v238, v238
	v_exp_f32_e32 v239, v239
	v_add_f32_e32 v156, v156, v238
	v_add_f32_e32 v156, v156, v239
	v_cvt_pk_bf16_f32 v238, v238, v239
	s_waitcnt lgkmcnt(12)
	v_mfma_f32_32x32x16_bf16 v[34:49], v[200:203], v[86:89], v[104:119]
	ds_read_b64_tr_b16 v[200:201], v159 offset:37888
	ds_read_b64_tr_b16 v[202:203], v159 offset:38400
	v_exp_f32_e32 v240, v240
	v_exp_f32_e32 v241, v241
	v_add_f32_e32 v157, v157, v240
	v_add_f32_e32 v157, v157, v241
	v_cvt_pk_bf16_f32 v239, v240, v241
	s_waitcnt lgkmcnt(13)
	v_mfma_f32_32x32x16_bf16 v[50:65], v[204:207], v[82:85], v[50:65]
	ds_read_b64_tr_b16 v[204:205], v159 offset:38912
	ds_read_b64_tr_b16 v[206:207], v159 offset:39424
	v_exp_f32_e32 v242, v242
	v_exp_f32_e32 v243, v243
	v_add_f32_e32 v156, v156, v242
	v_add_f32_e32 v156, v156, v243
	v_cvt_pk_bf16_f32 v240, v242, v243
	s_waitcnt lgkmcnt(14)
	v_mfma_f32_32x32x16_bf16 v[34:49], v[208:211], v[82:85], v[34:49]
	ds_read_b64_tr_b16 v[208:209], v159 offset:39936
	ds_read_b64_tr_b16 v[210:211], v159 offset:40448
	v_exp_f32_e32 v244, v244
	v_exp_f32_e32 v245, v245
	v_add_f32_e32 v157, v157, v244
	v_add_f32_e32 v157, v157, v245
	v_cvt_pk_bf16_f32 v241, v244, v245
	s_waitcnt lgkmcnt(15)
	v_mfma_f32_32x32x16_bf16 v[50:65], v[212:215], v[78:81], v[50:65]
	ds_read_b64_tr_b16 v[212:213], v159 offset:40960
	ds_read_b64_tr_b16 v[214:215], v159 offset:41472
	v_exp_f32_e32 v246, v246
	v_exp_f32_e32 v247, v247
	v_add_f32_e32 v156, v156, v246
	v_add_f32_e32 v156, v156, v247
	v_cvt_pk_bf16_f32 v242, v246, v247
	s_waitcnt lgkmcnt(15)
	v_mfma_f32_32x32x16_bf16 v[34:49], v[230:233], v[78:81], v[34:49]
	ds_read_b64_tr_b16 v[230:231], v159 offset:41984
	ds_read_b64_tr_b16 v[232:233], v159 offset:42496
	v_exp_f32_e32 v248, v248
	v_exp_f32_e32 v249, v249
	v_add_f32_e32 v157, v157, v248
	v_add_f32_e32 v157, v157, v249
	v_cvt_pk_bf16_f32 v243, v248, v249
	s_waitcnt lgkmcnt(15)
	v_mfma_f32_32x32x16_bf16 v[50:65], v[234:237], v[74:77], v[50:65]
	ds_read_b64_tr_b16 v[234:235], v159 offset:43008
	ds_read_b64_tr_b16 v[236:237], v159 offset:43520
	v_exp_f32_e32 v250, v250
	v_exp_f32_e32 v251, v251
	v_add_f32_e32 v156, v156, v250
	v_add_f32_e32 v156, v156, v251
	v_cvt_pk_bf16_f32 v244, v250, v251
	s_waitcnt lgkmcnt(15)
	v_mfma_f32_32x32x16_bf16 v[34:49], v[164:167], v[74:77], v[34:49]
	ds_read_b64_tr_b16 v[164:165], v159 offset:44032
	ds_read_b64_tr_b16 v[166:167], v159 offset:44544
	v_exp_f32_e32 v252, v252
	v_exp_f32_e32 v253, v253
	v_add_f32_e32 v157, v157, v252
	v_add_f32_e32 v157, v157, v253
	v_cvt_pk_bf16_f32 v245, v252, v253
	s_waitcnt lgkmcnt(15)
	v_mfma_f32_32x32x16_bf16 v[50:65], v[168:171], v[70:73], v[50:65]
	v_exp_f32_e32 v180, v180
	v_exp_f32_e32 v181, v181
	v_add_f32_e32 v156, v156, v180
	v_add_f32_e32 v156, v156, v181
	v_cvt_pk_bf16_f32 v180, v180, v181
	s_waitcnt lgkmcnt(15)
	v_mfma_f32_32x32x16_bf16 v[34:49], v[172:175], v[70:73], v[34:49]
	v_exp_f32_e32 v182, v182
	v_exp_f32_e32 v183, v183
	v_add_f32_e32 v157, v157, v182
	v_add_f32_e32 v157, v157, v183
	v_cvt_pk_bf16_f32 v181, v182, v183
	s_waitcnt lgkmcnt(15)
	v_mfma_f32_32x32x16_bf16 v[50:65], v[148:151], v[66:69], v[50:65]
	v_exp_f32_e32 v184, v184
	v_exp_f32_e32 v185, v185
	v_add_f32_e32 v156, v156, v184
	v_add_f32_e32 v156, v156, v185
	v_cvt_pk_bf16_f32 v182, v184, v185
	s_waitcnt lgkmcnt(15)
	v_mfma_f32_32x32x16_bf16 v[34:49], v[152:155], v[66:69], v[34:49]
	v_exp_f32_e32 v186, v186
	v_exp_f32_e32 v187, v187
	v_add_f32_e32 v157, v157, v186
	v_add_f32_e32 v157, v157, v187
	v_cvt_pk_bf16_f32 v183, v186, v187
	s_nop 1
	s_waitcnt lgkmcnt(0)
	v_mfma_f32_32x32x16_bf16 v[18:33], v[196:199], v[238:241], v[18:33]
	v_exp_f32_e32 v188, v188
	v_exp_f32_e32 v189, v189
	v_add_f32_e32 v156, v156, v188
	v_add_f32_e32 v156, v156, v189
	v_cvt_pk_bf16_f32 v184, v188, v189
	s_nop 1
	v_mfma_f32_32x32x16_bf16 v[2:17], v[212:215], v[238:241], v[2:17]
	s_mul_i32 s63, s61, 0x3000
	s_add_i32 s4, s62, 2
	s_cmp_ge_u32 s4, s90
	s_cbranch_scc1 .Lat_u2y_nodma
	s_add_i32 s4, s63, 0xffffd000
	s_cmp_lg_u32 s61, 0
	s_cselect_b32 s4, s4, 0x6000
	s_add_i32 s5, s4, s58
	s_mov_b32 m0, s5
	s_add_i32 s4, s4, s59
	global_load_lds_dwordx4 v[126:127], off
	s_mov_b32 m0, s4
	s_cmp_lt_u32 s56, 4
	s_cbranch_scc0 .Lat_u2y_nok2
	global_load_lds_dwordx4 v[122:123], off

; __device__ __forceinline__ void cmask(f32x16& p0, f32x16& p1, int jb, int qrel, int hi) {
;     const float NEG = -INFINITY; const int kb = 64 * jb + 4 * hi;
; #pragma unroll
;     for (int r = 0; r < 16; ++r) { const int kv = kb + (r & 3) + 8 * (r >> 2); if (kv > qrel) p0[r] = NEG; if (kv + 32 > qrel) p1[r] = NEG; }
; }
.Lat_u2y_nodma:
	v_lshl_add_u64 v[126:127], v[126:127], 0, s[34:35]
	v_lshl_add_u64 v[122:123], v[122:123], 0, s[20:21]
	v_lshl_add_u64 v[124:125], v[124:125], 0, s[34:35]
	v_exp_f32_e32 v190, v190
	v_exp_f32_e32 v191, v191
	v_add_f32_e32 v157, v157, v190
	v_add_f32_e32 v157, v157, v191
	v_cvt_pk_bf16_f32 v185, v190, v191
	s_nop 1
	v_mfma_f32_32x32x16_bf16 v[18:33], v[200:203], v[242:245], v[18:33]
	v_exp_f32_e32 v192, v192
	v_exp_f32_e32 v193, v193
	v_add_f32_e32 v156, v156, v192
	v_add_f32_e32 v156, v156, v193
	v_cvt_pk_bf16_f32 v186, v192, v193
	s_nop 1
	v_mfma_f32_32x32x16_bf16 v[2:17], v[230:233], v[242:245], v[2:17]
	v_exp_f32_e32 v194, v194
	v_exp_f32_e32 v195, v195
	v_add_f32_e32 v157, v157, v194
	v_add_f32_e32 v157, v157, v195
	v_cvt_pk_bf16_f32 v187, v194, v195
	s_nop 1
	v_mfma_f32_32x32x16_bf16 v[18:33], v[204:207], v[180:183], v[18:33]
	v_mfma_f32_32x32x16_bf16 v[2:17], v[234:237], v[180:183], v[2:17]
	v_mfma_f32_32x32x16_bf16 v[18:33], v[208:211], v[184:187], v[18:33]
	v_mfma_f32_32x32x16_bf16 v[2:17], v[164:167], v[184:187], v[2:17]
	v_add_f32_e32 v156, v156, v157
	v_add_f32_e32 v128, v128, v156
	s_cmp_lt_u32 s62, s91
	s_cbranch_scc1 .Lat_u2y_nomask
	s_sub_i32 s4, s62, s91
	s_lshl_b32 s4, s4, 6
	s_nop 7
	s_nop 7
	v_lshl_add_u32 v133, v142, 2, s4
	v_sub_u32_e32 v133, v145, v133
	v_cmp_gt_i32_e32 vcc, 0, v133
	s_nop 1
	v_cndmask_b32_e32 v50, v50, v220, vcc
	v_cmp_gt_i32_e32 vcc, 1, v133
	s_nop 1
	v_cndmask_b32_e32 v51, v51, v220, vcc
	v_cmp_gt_i32_e32 vcc, 2, v133
	s_nop 1
	v_cndmask_b32_e32 v52, v52, v220, vcc
	v_cmp_gt_i32_e32 vcc, 3, v133
	s_nop 1
	v_cndmask_b32_e32 v53, v53, v220, vcc
	v_cmp_gt_i32_e32 vcc, 8, v133
	s_nop 1
	v_cndmask_b32_e32 v54, v54, v220, vcc
	v_cmp_gt_i32_e32 vcc, 9, v133
	s_nop 1
	v_cndmask_b32_e32 v55, v55, v220, vcc
	v_cmp_gt_i32_e32 vcc, 10, v133
	s_nop 1
	v_cndmask_b32_e32 v56, v56, v220, vcc
	v_cmp_gt_i32_e32 vcc, 11, v133
	s_nop 1
	v_cndmask_b32_e32 v57, v57, v220, vcc
	v_cmp_gt_i32_e32 vcc, 16, v133
	s_nop 1
	v_cndmask_b32_e32 v58, v58, v220, vcc
	v_cmp_gt_i32_e32 vcc, 17, v133
	s_nop 1
	v_cndmask_b32_e32 v59, v59, v220, vcc
	v_cmp_gt_i32_e32 vcc, 18, v133
	s_nop 1
	v_cndmask_b32_e32 v60, v60, v220, vcc
	v_cmp_gt_i32_e32 vcc, 19, v133
	s_nop 1
	v_cndmask_b32_e32 v61, v61, v220, vcc
	v_cmp_gt_i32_e32 vcc, 24, v133
	s_nop 1
	v_cndmask_b32_e32 v62, v62, v220, vcc
	v_cmp_gt_i32_e32 vcc, 25, v133
	s_nop 1
	v_cndmask_b32_e32 v63, v63, v220, vcc
	v_cmp_gt_i32_e32 vcc, 26, v133
	s_nop 1
	v_cndmask_b32_e32 v64, v64, v220, vcc
	v_cmp_gt_i32_e32 vcc, 27, v133
	s_nop 1
	v_cndmask_b32_e32 v65, v65, v220, vcc
	v_cmp_gt_i32_e32 vcc, 32, v133
	s_nop 1
	v_cndmask_b32_e32 v34, v34, v220, vcc
	v_cmp_gt_i32_e32 vcc, 33, v133
	s_nop 1
	v_cndmask_b32_e32 v35, v35, v220, vcc
	v_cmp_gt_i32_e32 vcc, 34, v133
	s_nop 1
	v_cndmask_b32_e32 v36, v36, v220, vcc
	v_cmp_gt_i32_e32 vcc, 35, v133
	s_nop 1
	v_cndmask_b32_e32 v37, v37, v220, vcc
	v_cmp_gt_i32_e32 vcc, 40, v133
	s_nop 1
	v_cndmask_b32_e32 v38, v38, v220, vcc
	v_cmp_gt_i32_e32 vcc, 41, v133
	s_nop 1
	v_cndmask_b32_e32 v39, v39, v220, vcc
	v_cmp_gt_i32_e32 vcc, 42, v133
	s_nop 1
	v_cndmask_b32_e32 v40, v40, v220, vcc
	v_cmp_gt_i32_e32 vcc, 43, v133
	s_nop 1
	v_cndmask_b32_e32 v41, v41, v220, vcc
	v_cmp_gt_i32_e32 vcc, 48, v133
	s_nop 1
	v_cndmask_b32_e32 v42, v42, v220, vcc
	v_cmp_gt_i32_e32 vcc, 49, v133
	s_nop 1
	v_cndmask_b32_e32 v43, v43, v220, vcc
	v_cmp_gt_i32_e32 vcc, 50, v133
	s_nop 1
	v_cndmask_b32_e32 v44, v44, v220, vcc
	v_cmp_gt_i32_e32 vcc, 51, v133
	s_nop 1
	v_cndmask_b32_e32 v45, v45, v220, vcc
	v_cmp_gt_i32_e32 vcc, 56, v133
	s_nop 1
	v_cndmask_b32_e32 v46, v46, v220, vcc
	v_cmp_gt_i32_e32 vcc, 57, v133
	s_nop 1
	v_cndmask_b32_e32 v47, v47, v220, vcc
	v_cmp_gt_i32_e32 vcc, 58, v133
	s_nop 1
	v_cndmask_b32_e32 v48, v48, v220, vcc
	v_cmp_gt_i32_e32 vcc, 59, v133
	s_nop 1
	v_cndmask_b32_e32 v49, v49, v220, vcc

; #define LAS __attribute__((address_space(3)))
; __device__ __forceinline__ int crow(int r, int hi) { return (r & 3) + 8 * (r >> 2) + 4 * hi; }
; __device__ __forceinline__ unsigned cvtpk_s(float lo, float hi) { f32x2 v = {lo, hi}; typedef __bf16 bf16x2_t __attribute__((ext_vector_type(2))); bf16x2_t b = __builtin_convertvector(v, bf16x2_t); return __builtin_bit_cast(unsigned, b); }
; __device__ __forceinline__ void attn_unit(int b, int h, int qb, const bf16* Q, const bf16* __restrict__ Kn, const bf16* __restrict__ Kpe, const bf16* __restrict__ V, bf16* O, float* ASS, LAS char* shm) {
;     ...
;     { auto rr = __builtin_amdgcn_permlane32_swap(__float_as_uint(l_run), __float_as_uint(l_run), false, false); l_run = __uint_as_float(rr[0]) + __uint_as_float(rr[1]); }
;     if (hi == 0) wsf[32 + r32] = l_run; asm volatile("s_waitcnt lgkmcnt(0)" ::: "memory");
;     float rli[16];
; #pragma unroll
;     for (int r = 0; r < 16; ++r) rli[r] = __builtin_amdgcn_rcpf(wsf[32 + crow(r, hi)]);
;     bf16* Ow = O + (rowbase + q0 + wid * QBLK) * OP + h * 64;
;     { LAS unsigned short* stg = (LAS unsigned short*)(shm + LDS_OST) + wid * 2048;
; #pragma unroll
;       for (int r = 0; r < 16; ++r) { const int orow = crow(r, hi);
; #pragma unroll
;           for (int d0 = 0; d0 < 2; ++d0) stg[orow * 64 + d0 * 32 + r32] = (unsigned short)(cvtpk_s(o[d0][r] * rli[r], 0.f) & 0xffffu); }
;       asm volatile("s_waitcnt lgkmcnt(0)" ::: "memory");
; #pragma unroll
;       for (int i = 0; i < 4; ++i) { const int row = i * 8 + (lane >> 3), ch = lane & 7; const u32x4 v = *(const LAS u32x4*)(stg + row * 64 + ch * 8); *(u32x4*)(Ow + (long)row * OP + ch * 8) = v;
;           float sq = 0.f;
; #pragma unroll
;           for (int k = 0; k < 4; ++k) { const float a = __uint_as_float(v[k] << 16), bq = __uint_as_float(v[k] & 0xffff0000u); sq += a * a + bq * bq; }
;           sq += __shfl_xor(sq, 1); sq += __shfl_xor(sq, 2); sq += __shfl_xor(sq, 4);
;           if (ch == 0) ASS[(rowbase + q0 + wid * QBLK + row) * 8 + h] = sq; } }
.Lat_u2_tail:
	s_waitcnt lgkmcnt(0)
	s_lshr_b32 s4, s56, 1
	s_sub_u32 s4, s62, s4
	s_sub_u32 s4, s4, 1
	s_cmp_gt_i32 s4, s91
	s_cbranch_scc1 .Lat_u2t_skip
	s_lshl_b32 s4, s64, 13
	s_add_i32 s4, s4, 0x6000
	s_and_b32 s4, s4, 0x6000
	v_add_u32_e32 v159, s4, v143
	ds_read_b64_tr_b16 v[196:197], v159 offset:36864
	ds_read_b64_tr_b16 v[198:199], v159 offset:37376
	ds_read_b64_tr_b16 v[200:201], v159 offset:37888
	ds_read_b64_tr_b16 v[202:203], v159 offset:38400
	ds_read_b64_tr_b16 v[204:205], v159 offset:38912
	ds_read_b64_tr_b16 v[206:207], v159 offset:39424
	ds_read_b64_tr_b16 v[208:209], v159 offset:39936
	ds_read_b64_tr_b16 v[210:211], v159 offset:40448
	ds_read_b64_tr_b16 v[212:213], v159 offset:40960
	ds_read_b64_tr_b16 v[214:215], v159 offset:41472
	ds_read_b64_tr_b16 v[230:231], v159 offset:41984
	ds_read_b64_tr_b16 v[232:233], v159 offset:42496
	ds_read_b64_tr_b16 v[234:235], v159 offset:43008
	ds_read_b64_tr_b16 v[236:237], v159 offset:43520
	ds_read_b64_tr_b16 v[164:165], v159 offset:44032
	ds_read_b64_tr_b16 v[166:167], v159 offset:44544
	v_mov_b32_e32 v156, 0
	v_mov_b32_e32 v157, 0
	v_exp_f32_e32 v238, v238
	v_exp_f32_e32 v239, v239
	v_add_f32_e32 v156, v156, v238
	v_add_f32_e32 v156, v156, v239
	v_cvt_pk_bf16_f32 v238, v238, v239
	v_exp_f32_e32 v240, v240
	v_exp_f32_e32 v241, v241
	v_add_f32_e32 v157, v157, v240
	v_add_f32_e32 v157, v157, v241
	v_cvt_pk_bf16_f32 v239, v240, v241
	v_exp_f32_e32 v242, v242
	v_exp_f32_e32 v243, v243
	v_add_f32_e32 v156, v156, v242
	v_add_f32_e32 v156, v156, v243
	v_cvt_pk_bf16_f32 v240, v242, v243
	v_exp_f32_e32 v244, v244
	v_exp_f32_e32 v245, v245
	v_add_f32_e32 v157, v157, v244
	v_add_f32_e32 v157, v157, v245
	v_cvt_pk_bf16_f32 v241, v244, v245
	v_exp_f32_e32 v246, v246
	v_exp_f32_e32 v247, v247
	v_add_f32_e32 v156, v156, v246
	v_add_f32_e32 v156, v156, v247
	v_cvt_pk_bf16_f32 v242, v246, v247
	v_exp_f32_e32 v248, v248
	v_exp_f32_e32 v249, v249
	v_add_f32_e32 v157, v157, v248
	v_add_f32_e32 v157, v157, v249
	v_cvt_pk_bf16_f32 v243, v248, v249
	v_exp_f32_e32 v250, v250
	v_exp_f32_e32 v251, v251
	v_add_f32_e32 v156, v156, v250
	v_add_f32_e32 v156, v156, v251
	v_cvt_pk_bf16_f32 v244, v250, v251
	v_exp_f32_e32 v252, v252
	v_exp_f32_e32 v253, v253
	v_add_f32_e32 v157, v157, v252
	v_add_f32_e32 v157, v157, v253
	v_cvt_pk_bf16_f32 v245, v252, v253
	v_exp_f32_e32 v180, v180
	v_exp_f32_e32 v181, v181
	v_add_f32_e32 v156, v156, v180
	v_add_f32_e32 v156, v156, v181
	v_cvt_pk_bf16_f32 v180, v180, v181
	v_exp_f32_e32 v182, v182
	v_exp_f32_e32 v183, v183
	v_add_f32_e32 v157, v157, v182
	v_add_f32_e32 v157, v157, v183
	v_cvt_pk_bf16_f32 v181, v182, v183
	v_exp_f32_e32 v184, v184
	v_exp_f32_e32 v185, v185
	v_add_f32_e32 v156, v156, v184
	v_add_f32_e32 v156, v156, v185
	v_cvt_pk_bf16_f32 v182, v184, v185
	v_exp_f32_e32 v186, v186
	v_exp_f32_e32 v187, v187
	v_add_f32_e32 v157, v157, v186
	v_add_f32_e32 v157, v157, v187
	v_cvt_pk_bf16_f32 v183, v186, v187
	v_exp_f32_e32 v188, v188
	v_exp_f32_e32 v189, v189
	v_add_f32_e32 v156, v156, v188
	v_add_f32_e32 v156, v156, v189
	v_cvt_pk_bf16_f32 v184, v188, v189
	v_exp_f32_e32 v190, v190
	v_exp_f32_e32 v191, v191
	v_add_f32_e32 v157, v157, v190
	v_add_f32_e32 v157, v157, v191
	v_cvt_pk_bf16_f32 v185, v190, v191
	v_exp_f32_e32 v192, v192
	v_exp_f32_e32 v193, v193
	v_add_f32_e32 v156, v156, v192
	v_add_f32_e32 v156, v156, v193
	v_cvt_pk_bf16_f32 v186, v192, v193
	v_exp_f32_e32 v194, v194
	v_exp_f32_e32 v195, v195
	v_add_f32_e32 v157, v157, v194
	v_add_f32_e32 v157, v157, v195
	v_cvt_pk_bf16_f32 v187, v194, v195
	v_add_f32_e32 v156, v156, v157
	v_add_f32_e32 v128, v128, v156
	s_waitcnt lgkmcnt(0)
	v_mfma_f32_32x32x16_bf16 v[18:33], v[196:199], v[238:241], v[18:33]
	v_mfma_f32_32x32x16_bf16 v[2:17], v[212:215], v[238:241], v[2:17]
	v_mfma_f32_32x32x16_bf16 v[18:33], v[200:203], v[242:245], v[18:33]
	v_mfma_f32_32x32x16_bf16 v[2:17], v[230:233], v[242:245], v[2:17]
	v_mfma_f32_32x32x16_bf16 v[18:33], v[204:207], v[180:183], v[18:33]
	v_mfma_f32_32x32x16_bf16 v[2:17], v[234:237], v[180:183], v[2:17]
	v_mfma_f32_32x32x16_bf16 v[18:33], v[208:211], v[184:187], v[18:33]
	v_mfma_f32_32x32x16_bf16 v[2:17], v[164:167], v[184:187], v[2:17]
.Lat_u2t_skip:
	s_nop 7
	s_nop 7
	v_mov_b32_e32 v212, v128
	s_nop 1
	v_permlane32_swap_b32_e32 v128, v212
	s_nop 0
	v_add_f32_e32 v128, v128, v212
	v_rcp_f32_e32 v212, v128
	v_mov_b32_e32 v213, 0
	v_mul_f32_e32 v230, v18, v212
	v_mul_f32_e32 v231, v19, v212
	v_mul_f32_e32 v232, v20, v212
	v_mul_f32_e32 v233, v21, v212
	v_cvt_pk_bf16_f32 v196, v230, v231
	v_cvt_pk_bf16_f32 v197, v232, v233
	v_mul_f32_e32 v230, v22, v212
	v_mul_f32_e32 v231, v23, v212
	v_mul_f32_e32 v232, v24, v212
	v_mul_f32_e32 v233, v25, v212
	v_cvt_pk_bf16_f32 v198, v230, v231
	v_cvt_pk_bf16_f32 v199, v232, v233
	v_mul_f32_e32 v230, v26, v212
	v_mul_f32_e32 v231, v27, v212
	v_mul_f32_e32 v232, v28, v212
	v_mul_f32_e32 v233, v29, v212
	v_cvt_pk_bf16_f32 v200, v230, v231
	v_cvt_pk_bf16_f32 v201, v232, v233
	v_mul_f32_e32 v230, v30, v212
	v_mul_f32_e32 v231, v31, v212
	v_mul_f32_e32 v232, v32, v212
	v_mul_f32_e32 v233, v33, v212
	v_cvt_pk_bf16_f32 v202, v230, v231
	v_cvt_pk_bf16_f32 v203, v232, v233
	v_mul_f32_e32 v230, v2, v212
	v_mul_f32_e32 v231, v3, v212
	v_mul_f32_e32 v232, v4, v212
	v_mul_f32_e32 v233, v5, v212
	v_cvt_pk_bf16_f32 v204, v230, v231
	v_cvt_pk_bf16_f32 v205, v232, v233
	v_mul_f32_e32 v230, v6, v212
	v_mul_f32_e32 v231, v7, v212
	v_mul_f32_e32 v232, v8, v212
	v_mul_f32_e32 v233, v9, v212
	v_cvt_pk_bf16_f32 v206, v230, v231
	v_cvt_pk_bf16_f32 v207, v232, v233
	v_mul_f32_e32 v230, v10, v212
	v_mul_f32_e32 v231, v11, v212
	v_mul_f32_e32 v232, v12, v212
; #define LAS __attribute__((address_space(3)))
; __device__ __forceinline__ int crow(int r, int hi) { return (r & 3) + 8 * (r >> 2) + 4 * hi; }
; __device__ __forceinline__ unsigned cvtpk_s(float lo, float hi) { f32x2 v = {lo, hi}; typedef __bf16 bf16x2_t __attribute__((ext_vector_type(2))); bf16x2_t b = __builtin_convertvector(v, bf16x2_t); return __builtin_bit_cast(unsigned, b); }
; __device__ __forceinline__ void attn_unit(int b, int h, int qb, const bf16* Q, const bf16* __restrict__ Kn, const bf16* __restrict__ Kpe, const bf16* __restrict__ V, bf16* O, float* ASS, LAS char* shm) {
;     ...
;     bf16* Ow = O + (rowbase + q0 + wid * QBLK) * OP + h * 64;
;     { LAS unsigned short* stg = (LAS unsigned short*)(shm + LDS_OST) + wid * 2048;
; #pragma unroll
;       for (int r = 0; r < 16; ++r) { const int orow = crow(r, hi);
; #pragma unroll
;           for (int d0 = 0; d0 < 2; ++d0) stg[orow * 64 + d0 * 32 + r32] = (unsigned short)(cvtpk_s(o[d0][r] * rli[r], 0.f) & 0xffffu); }
;       asm volatile("s_waitcnt lgkmcnt(0)" ::: "memory");
; #pragma unroll
;       for (int i = 0; i < 4; ++i) { const int row = i * 8 + (lane >> 3), ch = lane & 7; const u32x4 v = *(const LAS u32x4*)(stg + row * 64 + ch * 8); *(u32x4*)(Ow + (long)row * OP + ch * 8) = v;
;           float sq = 0.f;
; #pragma unroll
;           for (int k = 0; k < 4; ++k) { const float a = __uint_as_float(v[k] << 16), bq = __uint_as_float(v[k] & 0xffff0000u); sq += a * a + bq * bq; }
;           sq += __shfl_xor(sq, 1); sq += __shfl_xor(sq, 2); sq += __shfl_xor(sq, 4);
;           if (ch == 0) ASS[(rowbase + q0 + wid * QBLK + row) * 8 + h] = sq; } }
	v_mul_f32_e32 v233, v13, v212
	v_cvt_pk_bf16_f32 v208, v230, v231
	v_cvt_pk_bf16_f32 v209, v232, v233
	v_mul_f32_e32 v230, v14, v212
	v_mul_f32_e32 v231, v15, v212
	v_mul_f32_e32 v232, v16, v212
	v_mul_f32_e32 v233, v17, v212
	v_cvt_pk_bf16_f32 v210, v230, v231
	v_cvt_pk_bf16_f32 v211, v232, v233
	s_nop 1
	v_permlane32_swap_b32_e32 v196, v198
	v_permlane32_swap_b32_e32 v197, v199
	v_permlane32_swap_b32_e32 v200, v202
	v_permlane32_swap_b32_e32 v201, v203
	v_permlane32_swap_b32_e32 v204, v206
	v_permlane32_swap_b32_e32 v205, v207
	v_permlane32_swap_b32_e32 v208, v210
	v_permlane32_swap_b32_e32 v209, v211
	s_lshl_b64 s[4:5], s[52:53], 11
	s_add_u32 s4, s4, s80
	s_addc_u32 s5, s5, s81
	s_lshl_b32 s63, s68, 7
	s_add_u32 s4, s4, s63
	s_addc_u32 s5, s5, 0
	v_lshlrev_b32_e32 v234, 11, v141
	v_lshl_or_b32 v234, v142, 4, v234
	global_store_dwordx4 v234, v[196:199], s[4:5]
	global_store_dwordx4 v234, v[200:203], s[4:5] offset:32
	global_store_dwordx4 v234, v[204:207], s[4:5] offset:64
	global_store_dwordx4 v234, v[208:211], s[4:5] offset:96
	v_lshlrev_b32_e32 v230, 16, v196
	v_and_b32_e32 v231, 0xffff0000, v196
	v_fmac_f32_e32 v213, v230, v230
	v_fmac_f32_e32 v213, v231, v231
	v_lshlrev_b32_e32 v230, 16, v197
	v_and_b32_e32 v231, 0xffff0000, v197
	v_fmac_f32_e32 v213, v230, v230
	v_fmac_f32_e32 v213, v231, v231
	v_lshlrev_b32_e32 v230, 16, v198
	v_and_b32_e32 v231, 0xffff0000, v198
	v_fmac_f32_e32 v213, v230, v230
	v_fmac_f32_e32 v213, v231, v231
	v_lshlrev_b32_e32 v230, 16, v199
	v_and_b32_e32 v231, 0xffff0000, v199
	v_fmac_f32_e32 v213, v230, v230
	v_fmac_f32_e32 v213, v231, v231
	v_lshlrev_b32_e32 v230, 16, v200
	v_and_b32_e32 v231, 0xffff0000, v200
	v_fmac_f32_e32 v213, v230, v230
	v_fmac_f32_e32 v213, v231, v231
	v_lshlrev_b32_e32 v230, 16, v201
	v_and_b32_e32 v231, 0xffff0000, v201
	v_fmac_f32_e32 v213, v230, v230
	v_fmac_f32_e32 v213, v231, v231
	v_lshlrev_b32_e32 v230, 16, v202
	v_and_b32_e32 v231, 0xffff0000, v202
	v_fmac_f32_e32 v213, v230, v230
	v_fmac_f32_e32 v213, v231, v231
	v_lshlrev_b32_e32 v230, 16, v203
	v_and_b32_e32 v231, 0xffff0000, v203
	v_fmac_f32_e32 v213, v230, v230
	v_fmac_f32_e32 v213, v231, v231
	v_lshlrev_b32_e32 v230, 16, v204
	v_and_b32_e32 v231, 0xffff0000, v204
	v_fmac_f32_e32 v213, v230, v230
	v_fmac_f32_e32 v213, v231, v231
	v_lshlrev_b32_e32 v230, 16, v205
	v_and_b32_e32 v231, 0xffff0000, v205
	v_fmac_f32_e32 v213, v230, v230
	v_fmac_f32_e32 v213, v231, v231
	v_lshlrev_b32_e32 v230, 16, v206
	v_and_b32_e32 v231, 0xffff0000, v206
	v_fmac_f32_e32 v213, v230, v230
	v_fmac_f32_e32 v213, v231, v231
	v_lshlrev_b32_e32 v230, 16, v207
	v_and_b32_e32 v231, 0xffff0000, v207
	v_fmac_f32_e32 v213, v230, v230
	v_fmac_f32_e32 v213, v231, v231
	v_lshlrev_b32_e32 v230, 16, v208
	v_and_b32_e32 v231, 0xffff0000, v208
	v_fmac_f32_e32 v213, v230, v230
	v_fmac_f32_e32 v213, v231, v231
	v_lshlrev_b32_e32 v230, 16, v209
	v_and_b32_e32 v231, 0xffff0000, v209
	v_fmac_f32_e32 v213, v230, v230
	v_fmac_f32_e32 v213, v231, v231
	v_lshlrev_b32_e32 v230, 16, v210
	v_and_b32_e32 v231, 0xffff0000, v210
	v_fmac_f32_e32 v213, v230, v230
	v_fmac_f32_e32 v213, v231, v231
	v_lshlrev_b32_e32 v230, 16, v211
	v_and_b32_e32 v231, 0xffff0000, v211
	v_fmac_f32_e32 v213, v230, v230
	v_fmac_f32_e32 v213, v231, v231
	v_mov_b32_e32 v230, v213
	s_nop 1
	v_permlane32_swap_b32_e32 v213, v230
	s_nop 0
	v_add_f32_e32 v213, v213, v230
	s_lshl_b64 s[4:5], s[52:53], 5
	s_add_u32 s4, s4, s82
	s_addc_u32 s5, s5, s83
	s_lshl_b32 s63, s68, 2
	s_add_u32 s4, s4, s63
	s_addc_u32 s5, s5, 0
	v_lshlrev_b32_e32 v235, 5, v141
	v_cmp_gt_u32_e32 vcc, 32, v140
	s_and_saveexec_b64 s[54:55], vcc
	global_store_dword v235, v213, s[4:5]
	s_or_b64 exec, exec, s[54:55]
	s_mov_b32 m0, s65
	s_branch .LBB0_869
.Lat_u2x_rare:
	s_nop 15
	v_mov_b32_e32 v132, v131
	s_nop 1
	v_permlane32_swap_b32_e32 v131, v132
	s_nop 0
	v_max_f32_e32 v131, v131, v132
	v_max_f32_e32 v132, 0, v131
	v_exp_f32_e64 v133, -v132
	v_add_f32_e32 v130, v130, v132
	s_nop 0
	v_mul_f32_e32 v128, v128, v133
	v_sub_f32_e32 v104, v104, v132
	v_sub_f32_e32 v105, v105, v132
	v_sub_f32_e32 v106, v106, v132
	v_sub_f32_e32 v107, v107, v132
	v_sub_f32_e32 v108, v108, v132
	v_sub_f32_e32 v109, v109, v132
	v_sub_f32_e32 v110, v110, v132
	v_sub_f32_e32 v111, v111, v132
	v_sub_f32_e32 v112, v112, v132
	v_sub_f32_e32 v113, v113, v132
	v_sub_f32_e32 v114, v114, v132
	v_sub_f32_e32 v115, v115, v132
	v_sub_f32_e32 v116, v116, v132
	v_sub_f32_e32 v117, v117, v132
	v_sub_f32_e32 v118, v118, v132
	v_sub_f32_e32 v119, v119, v132
	v_sub_f32_e32 v238, v238, v132
	v_sub_f32_e32 v239, v239, v132
	v_sub_f32_e32 v240, v240, v132
	v_sub_f32_e32 v241, v241, v132
	v_sub_f32_e32 v242, v242, v132
	v_sub_f32_e32 v243, v243, v132
	v_sub_f32_e32 v244, v244, v132
	v_sub_f32_e32 v245, v245, v132
	v_sub_f32_e32 v246, v246, v132
	v_sub_f32_e32 v247, v247, v132
	v_sub_f32_e32 v248, v248, v132
	v_sub_f32_e32 v249, v249, v132
	v_sub_f32_e32 v250, v250, v132
	v_sub_f32_e32 v251, v251, v132
	v_sub_f32_e32 v252, v252, v132
	v_sub_f32_e32 v253, v253, v132
	v_sub_f32_e32 v180, v180, v132
	v_sub_f32_e32 v181, v181, v132
	v_sub_f32_e32 v182, v182, v132
	v_sub_f32_e32 v183, v183, v132
	v_sub_f32_e32 v184, v184, v132
	v_sub_f32_e32 v185, v185, v132
	v_sub_f32_e32 v186, v186, v132
	v_sub_f32_e32 v187, v187, v132
	v_sub_f32_e32 v188, v188, v132
	v_sub_f32_e32 v189, v189, v132
	v_sub_f32_e32 v190, v190, v132
	v_sub_f32_e32 v191, v191, v132
	v_sub_f32_e32 v192, v192, v132
	v_sub_f32_e32 v193, v193, v132
	v_sub_f32_e32 v194, v194, v132
	v_sub_f32_e32 v195, v195, v132
	v_mul_f32_e32 v18, v18, v133
	v_mul_f32_e32 v2, v2, v133
	v_mul_f32_e32 v19, v19, v133
	v_mul_f32_e32 v3, v3, v133
	v_mul_f32_e32 v20, v20, v133
	v_mul_f32_e32 v4, v4, v133
	v_mul_f32_e32 v21, v21, v133
	v_mul_f32_e32 v5, v5, v133
	v_mul_f32_e32 v22, v22, v133
	v_mul_f32_e32 v6, v6, v133
	v_mul_f32_e32 v23, v23, v133
	v_mul_f32_e32 v7, v7, v133
	v_mul_f32_e32 v24, v24, v133
	v_mul_f32_e32 v8, v8, v133
	v_mul_f32_e32 v25, v25, v133
	v_mul_f32_e32 v9, v9, v133
	v_mul_f32_e32 v26, v26, v133
	v_mul_f32_e32 v10, v10, v133
	v_mul_f32_e32 v27, v27, v133
	v_mul_f32_e32 v11, v11, v133
	v_mul_f32_e32 v28, v28, v133
	v_mul_f32_e32 v12, v12, v133
	v_mul_f32_e32 v29, v29, v133
	v_mul_f32_e32 v13, v13, v133
	v_mul_f32_e32 v30, v30, v133
	v_mul_f32_e32 v14, v14, v133
	v_mul_f32_e32 v31, v31, v133
	v_mul_f32_e32 v15, v15, v133
	v_mul_f32_e32 v32, v32, v133
	v_mul_f32_e32 v16, v16, v133
	v_mul_f32_e32 v33, v33, v133
	v_mul_f32_e32 v17, v17, v133
	s_branch .Lat_u2x_back
.Lat_u2y_rare:
	s_nop 15
	v_mov_b32_e32 v132, v131
	s_nop 1
	v_permlane32_swap_b32_e32 v131, v132
	s_nop 0
	v_max_f32_e32 v131, v131, v132
	v_max_f32_e32 v132, 0, v131
	v_exp_f32_e64 v133, -v132
	v_add_f32_e32 v130, v130, v132
	s_nop 0
	v_mul_f32_e32 v128, v128, v133
	v_sub_f32_e32 v104, v104, v132
	v_sub_f32_e32 v105, v105, v132
	v_sub_f32_e32 v106, v106, v132
	v_sub_f32_e32 v107, v107, v132
	v_sub_f32_e32 v108, v108, v132
	v_sub_f32_e32 v109, v109, v132
	v_sub_f32_e32 v110, v110, v132
	v_sub_f32_e32 v111, v111, v132
	v_sub_f32_e32 v112, v112, v132
	v_sub_f32_e32 v113, v113, v132
	v_sub_f32_e32 v114, v114, v132
	v_sub_f32_e32 v115, v115, v132
	v_sub_f32_e32 v116, v116, v132
	v_sub_f32_e32 v117, v117, v132
	v_sub_f32_e32 v118, v118, v132
	v_sub_f32_e32 v119, v119, v132
	v_sub_f32_e32 v50, v50, v132
	v_sub_f32_e32 v51, v51, v132
	v_sub_f32_e32 v52, v52, v132
	v_sub_f32_e32 v53, v53, v132
	v_sub_f32_e32 v54, v54, v132
	v_sub_f32_e32 v55, v55, v132
	v_sub_f32_e32 v56, v56, v132
	v_sub_f32_e32 v57, v57, v132
	v_sub_f32_e32 v58, v58, v132
	v_sub_f32_e32 v59, v59, v132
	v_sub_f32_e32 v60, v60, v132
	v_sub_f32_e32 v61, v61, v132
	v_sub_f32_e32 v62, v62, v132
	v_sub_f32_e32 v63, v63, v132
	v_sub_f32_e32 v64, v64, v132
	v_sub_f32_e32 v65, v65, v132
	v_sub_f32_e32 v34, v34, v132
	v_sub_f32_e32 v35, v35, v132
	v_sub_f32_e32 v36, v36, v132
	v_sub_f32_e32 v37, v37, v132
	v_sub_f32_e32 v38, v38, v132
	v_sub_f32_e32 v39, v39, v132
	v_sub_f32_e32 v40, v40, v132
	v_sub_f32_e32 v41, v41, v132
	v_sub_f32_e32 v42, v42, v132
	v_sub_f32_e32 v43, v43, v132
	v_sub_f32_e32 v44, v44, v132
	v_sub_f32_e32 v45, v45, v132
	v_sub_f32_e32 v46, v46, v132
	v_sub_f32_e32 v47, v47, v132
	v_sub_f32_e32 v48, v48, v132
	v_sub_f32_e32 v49, v49, v132
	v_mul_f32_e32 v18, v18, v133
	v_mul_f32_e32 v2, v2, v133
	v_mul_f32_e32 v19, v19, v133
	v_mul_f32_e32 v3, v3, v133
	v_mul_f32_e32 v20, v20, v133
	v_mul_f32_e32 v4, v4, v133
	v_mul_f32_e32 v21, v21, v133
	v_mul_f32_e32 v5, v5, v133
	v_mul_f32_e32 v22, v22, v133
	v_mul_f32_e32 v6, v6, v133
	v_mul_f32_e32 v23, v23, v133
	v_mul_f32_e32 v7, v7, v133
	v_mul_f32_e32 v24, v24, v133
	v_mul_f32_e32 v8, v8, v133
	v_mul_f32_e32 v25, v25, v133
	v_mul_f32_e32 v9, v9, v133
	v_mul_f32_e32 v26, v26, v133
	v_mul_f32_e32 v10, v10, v133
	v_mul_f32_e32 v27, v27, v133
	v_mul_f32_e32 v11, v11, v133
	v_mul_f32_e32 v28, v28, v133
	v_mul_f32_e32 v12, v12, v133
	v_mul_f32_e32 v29, v29, v133
	v_mul_f32_e32 v13, v13, v133
	v_mul_f32_e32 v30, v30, v133
	v_mul_f32_e32 v14, v14, v133
	v_mul_f32_e32 v31, v31, v133
	v_mul_f32_e32 v15, v15, v133
	v_mul_f32_e32 v32, v32, v133
	v_mul_f32_e32 v16, v16, v133
	v_mul_f32_e32 v33, v33, v133
	v_mul_f32_e32 v17, v17, v133
	s_branch .Lat_u2y_back
.Lat_u2x_noqk:
	s_lshr_b32 s4, s56, 1
	s_sub_u32 s4, s62, s4
	s_sub_u32 s4, s4, 1
	s_cmp_gt_i32 s4, s91
	s_cbranch_scc1 .Lat_u2x_idle
	s_lshl_b32 s4, s64, 13
	s_add_i32 s4, s4, 0x6000
	s_and_b32 s4, s4, 0x6000
	v_add_u32_e32 v159, s4, v143
	ds_read_b64_tr_b16 v[196:197], v159 offset:36864
	ds_read_b64_tr_b16 v[198:199], v159 offset:37376
	ds_read_b64_tr_b16 v[200:201], v159 offset:37888
	ds_read_b64_tr_b16 v[202:203], v159 offset:38400
	ds_read_b64_tr_b16 v[204:205], v159 offset:38912
	ds_read_b64_tr_b16 v[206:207], v159 offset:39424
	ds_read_b64_tr_b16 v[208:209], v159 offset:39936
	ds_read_b64_tr_b16 v[210:211], v159 offset:40448
	ds_read_b64_tr_b16 v[212:213], v159 offset:40960
	ds_read_b64_tr_b16 v[214:215], v159 offset:41472
	ds_read_b64_tr_b16 v[230:231], v159 offset:41984
	ds_read_b64_tr_b16 v[232:233], v159 offset:42496
	ds_read_b64_tr_b16 v[234:235], v159 offset:43008
	ds_read_b64_tr_b16 v[236:237], v159 offset:43520
	ds_read_b64_tr_b16 v[164:165], v159 offset:44032
	ds_read_b64_tr_b16 v[166:167], v159 offset:44544
	v_mov_b32_e32 v156, 0
	v_mov_b32_e32 v157, 0
	v_exp_f32_e32 v50, v50
	v_exp_f32_e32 v51, v51
	v_add_f32_e32 v156, v156, v50
	v_add_f32_e32 v156, v156, v51
	v_cvt_pk_bf16_f32 v50, v50, v51
	v_exp_f32_e32 v52, v52
	v_exp_f32_e32 v53, v53
	v_add_f32_e32 v157, v157, v52
	v_add_f32_e32 v157, v157, v53
	v_cvt_pk_bf16_f32 v51, v52, v53
	v_exp_f32_e32 v54, v54
	v_exp_f32_e32 v55, v55
	v_add_f32_e32 v156, v156, v54
	v_add_f32_e32 v156, v156, v55
	v_cvt_pk_bf16_f32 v52, v54, v55
	v_exp_f32_e32 v56, v56
	v_exp_f32_e32 v57, v57
	v_add_f32_e32 v157, v157, v56
	v_add_f32_e32 v157, v157, v57
	v_cvt_pk_bf16_f32 v53, v56, v57
	v_exp_f32_e32 v58, v58
	v_exp_f32_e32 v59, v59
	v_add_f32_e32 v156, v156, v58
	v_add_f32_e32 v156, v156, v59
	v_cvt_pk_bf16_f32 v54, v58, v59
	v_exp_f32_e32 v60, v60
	v_exp_f32_e32 v61, v61
	v_add_f32_e32 v157, v157, v60
	v_add_f32_e32 v157, v157, v61
	v_cvt_pk_bf16_f32 v55, v60, v61
	v_exp_f32_e32 v62, v62
	v_exp_f32_e32 v63, v63
	v_add_f32_e32 v156, v156, v62
	v_add_f32_e32 v156, v156, v63
	v_cvt_pk_bf16_f32 v56, v62, v63
	v_exp_f32_e32 v64, v64
	v_exp_f32_e32 v65, v65
	v_add_f32_e32 v157, v157, v64
	v_add_f32_e32 v157, v157, v65
	v_cvt_pk_bf16_f32 v57, v64, v65
	s_nop 1
	s_waitcnt lgkmcnt(0)
	v_mfma_f32_32x32x16_bf16 v[18:33], v[196:199], v[50:53], v[18:33]
	v_exp_f32_e32 v34, v34
	v_exp_f32_e32 v35, v35
	v_add_f32_e32 v156, v156, v34
	v_add_f32_e32 v156, v156, v35
	v_cvt_pk_bf16_f32 v34, v34, v35
	v_exp_f32_e32 v36, v36
	v_exp_f32_e32 v37, v37
	v_add_f32_e32 v157, v157, v36
	v_add_f32_e32 v157, v157, v37
	v_cvt_pk_bf16_f32 v35, v36, v37
	v_mfma_f32_32x32x16_bf16 v[2:17], v[212:215], v[50:53], v[2:17]
	v_exp_f32_e32 v38, v38
	v_exp_f32_e32 v39, v39
	v_add_f32_e32 v156, v156, v38
	v_add_f32_e32 v156, v156, v39
	v_cvt_pk_bf16_f32 v36, v38, v39
	v_exp_f32_e32 v40, v40
	v_exp_f32_e32 v41, v41
	v_add_f32_e32 v157, v157, v40
	v_add_f32_e32 v157, v157, v41
	v_cvt_pk_bf16_f32 v37, v40, v41
	v_mfma_f32_32x32x16_bf16 v[18:33], v[200:203], v[54:57], v[18:33]
	v_exp_f32_e32 v42, v42
	v_exp_f32_e32 v43, v43
	v_add_f32_e32 v156, v156, v42
	v_add_f32_e32 v156, v156, v43
	v_cvt_pk_bf16_f32 v38, v42, v43
	v_exp_f32_e32 v44, v44
	v_exp_f32_e32 v45, v45
	v_add_f32_e32 v157, v157, v44
	v_add_f32_e32 v157, v157, v45
	v_cvt_pk_bf16_f32 v39, v44, v45
	v_mfma_f32_32x32x16_bf16 v[2:17], v[230:233], v[54:57], v[2:17]
	v_exp_f32_e32 v46, v46
	v_exp_f32_e32 v47, v47
	v_add_f32_e32 v156, v156, v46
	v_add_f32_e32 v156, v156, v47
	v_cvt_pk_bf16_f32 v40, v46, v47
	v_exp_f32_e32 v48, v48
	v_exp_f32_e32 v49, v49
	v_add_f32_e32 v157, v157, v48
	v_add_f32_e32 v157, v157, v49
	v_cvt_pk_bf16_f32 v41, v48, v49
	s_nop 1
	v_mfma_f32_32x32x16_bf16 v[18:33], v[204:207], v[34:37], v[18:33]
	v_mfma_f32_32x32x16_bf16 v[2:17], v[234:237], v[34:37], v[2:17]
	v_mfma_f32_32x32x16_bf16 v[18:33], v[208:211], v[38:41], v[18:33]
	v_mfma_f32_32x32x16_bf16 v[2:17], v[164:167], v[38:41], v[2:17]
	v_add_f32_e32 v156, v156, v157
	v_add_f32_e32 v128, v128, v156

.Lat_u2y_noqk:
	s_lshr_b32 s4, s56, 1
	s_sub_u32 s4, s62, s4
	s_sub_u32 s4, s4, 1
	s_cmp_gt_i32 s4, s91
	s_cbranch_scc1 .Lat_u2y_idle
	s_lshl_b32 s4, s64, 13
	s_add_i32 s4, s4, 0x6000
	s_and_b32 s4, s4, 0x6000
	v_add_u32_e32 v159, s4, v143
	ds_read_b64_tr_b16 v[196:197], v159 offset:36864
	ds_read_b64_tr_b16 v[198:199], v159 offset:37376
	ds_read_b64_tr_b16 v[200:201], v159 offset:37888
	ds_read_b64_tr_b16 v[202:203], v159 offset:38400
	ds_read_b64_tr_b16 v[204:205], v159 offset:38912
	ds_read_b64_tr_b16 v[206:207], v159 offset:39424
	ds_read_b64_tr_b16 v[208:209], v159 offset:39936
	ds_read_b64_tr_b16 v[210:211], v159 offset:40448
	ds_read_b64_tr_b16 v[212:213], v159 offset:40960
	ds_read_b64_tr_b16 v[214:215], v159 offset:41472
	ds_read_b64_tr_b16 v[230:231], v159 offset:41984
	ds_read_b64_tr_b16 v[232:233], v159 offset:42496
	ds_read_b64_tr_b16 v[234:235], v159 offset:43008
	ds_read_b64_tr_b16 v[236:237], v159 offset:43520
	ds_read_b64_tr_b16 v[164:165], v159 offset:44032
	ds_read_b64_tr_b16 v[166:167], v159 offset:44544
	v_mov_b32_e32 v156, 0
	v_mov_b32_e32 v157, 0
	v_exp_f32_e32 v238, v238
	v_exp_f32_e32 v239, v239
	v_add_f32_e32 v156, v156, v238
	v_add_f32_e32 v156, v156, v239
	v_cvt_pk_bf16_f32 v238, v238, v239
	v_exp_f32_e32 v240, v240
	v_exp_f32_e32 v241, v241
	v_add_f32_e32 v157, v157, v240
	v_add_f32_e32 v157, v157, v241
	v_cvt_pk_bf16_f32 v239, v240, v241
	v_exp_f32_e32 v242, v242
	v_exp_f32_e32 v243, v243
	v_add_f32_e32 v156, v156, v242
	v_add_f32_e32 v156, v156, v243
	v_cvt_pk_bf16_f32 v240, v242, v243
	v_exp_f32_e32 v244, v244
	v_exp_f32_e32 v245, v245
	v_add_f32_e32 v157, v157, v244
	v_add_f32_e32 v157, v157, v245
	v_cvt_pk_bf16_f32 v241, v244, v245
	v_exp_f32_e32 v246, v246
	v_exp_f32_e32 v247, v247
	v_add_f32_e32 v156, v156, v246
	v_add_f32_e32 v156, v156, v247
	v_cvt_pk_bf16_f32 v242, v246, v247
	v_exp_f32_e32 v248, v248
	v_exp_f32_e32 v249, v249
	v_add_f32_e32 v157, v157, v248
	v_add_f32_e32 v157, v157, v249
	v_cvt_pk_bf16_f32 v243, v248, v249
	v_exp_f32_e32 v250, v250
	v_exp_f32_e32 v251, v251
	v_add_f32_e32 v156, v156, v250
	v_add_f32_e32 v156, v156, v251
	v_cvt_pk_bf16_f32 v244, v250, v251
	v_exp_f32_e32 v252, v252
	v_exp_f32_e32 v253, v253
	v_add_f32_e32 v157, v157, v252
	v_add_f32_e32 v157, v157, v253
	v_cvt_pk_bf16_f32 v245, v252, v253
	s_nop 1
	s_waitcnt lgkmcnt(0)
	v_mfma_f32_32x32x16_bf16 v[18:33], v[196:199], v[238:241], v[18:33]
	v_exp_f32_e32 v180, v180
	v_exp_f32_e32 v181, v181
	v_add_f32_e32 v156, v156, v180
	v_add_f32_e32 v156, v156, v181
	v_cvt_pk_bf16_f32 v180, v180, v181
	v_exp_f32_e32 v182, v182
	v_exp_f32_e32 v183, v183
	v_add_f32_e32 v157, v157, v182
	v_add_f32_e32 v157, v157, v183
	v_cvt_pk_bf16_f32 v181, v182, v183
	v_mfma_f32_32x32x16_bf16 v[2:17], v[212:215], v[238:241], v[2:17]
	v_exp_f32_e32 v184, v184
	v_exp_f32_e32 v185, v185
	v_add_f32_e32 v156, v156, v184
	v_add_f32_e32 v156, v156, v185
	v_cvt_pk_bf16_f32 v182, v184, v185
	v_exp_f32_e32 v186, v186
	v_exp_f32_e32 v187, v187
	v_add_f32_e32 v157, v157, v186
	v_add_f32_e32 v157, v157, v187
	v_cvt_pk_bf16_f32 v183, v186, v187
	v_mfma_f32_32x32x16_bf16 v[18:33], v[200:203], v[242:245], v[18:33]
	v_exp_f32_e32 v188, v188
	v_exp_f32_e32 v189, v189
	v_add_f32_e32 v156, v156, v188
	v_add_f32_e32 v156, v156, v189
	v_cvt_pk_bf16_f32 v184, v188, v189
	v_exp_f32_e32 v190, v190
	v_exp_f32_e32 v191, v191
	v_add_f32_e32 v157, v157, v190
	v_add_f32_e32 v157, v157, v191
	v_cvt_pk_bf16_f32 v185, v190, v191
	v_mfma_f32_32x32x16_bf16 v[2:17], v[230:233], v[242:245], v[2:17]
	v_exp_f32_e32 v192, v192
	v_exp_f32_e32 v193, v193
	v_add_f32_e32 v156, v156, v192
	v_add_f32_e32 v156, v156, v193
	v_cvt_pk_bf16_f32 v186, v192, v193
	v_exp_f32_e32 v194, v194
	v_exp_f32_e32 v195, v195
	v_add_f32_e32 v157, v157, v194
	v_add_f32_e32 v157, v157, v195
	v_cvt_pk_bf16_f32 v187, v194, v195
	s_nop 1
	v_mfma_f32_32x32x16_bf16 v[18:33], v[204:207], v[180:183], v[18:33]
	v_mfma_f32_32x32x16_bf16 v[2:17], v[234:237], v[180:183], v[2:17]
	v_mfma_f32_32x32x16_bf16 v[18:33], v[208:211], v[184:187], v[18:33]
	v_mfma_f32_32x32x16_bf16 v[2:17], v[164:167], v[184:187], v[2:17]
	v_add_f32_e32 v156, v156, v157
	v_add_f32_e32 v128, v128, v156
